# attention PV block: every lgkmcnt(0) before a V-fragment group replaced by counted per-MFMA waits (lgkmcnt 6/6/6/6 and 6/4/2/0 for the last group)
# speedup vs baseline: 1.0086x; 1.0021x over previous
; __device__ __forceinline__ void finishSM(f32x16& p0, f32x16& p1, float alpha, float& l_reg, bf16x8& pa0, bf16x8& pa1, bf16x8& pa2, bf16x8& pa3) {
; #pragma unroll
;     for (int r = 0; r < 16; ++r) p1[r] = __builtin_amdgcn_exp2f(p1[r]);
;     float ps = 0;
; #pragma unroll
;     for (int r = 0; r < 16; ++r) ps += p0[r];
; #pragma unroll
;     for (int r = 0; r < 16; ++r) ps += p1[r];
;     { auto rr = __builtin_amdgcn_permlane32_swap(__float_as_uint(ps), __float_as_uint(ps), false, false);
;       ps = __uint_as_float(rr[0]) + __uint_as_float(rr[1]); }
;     l_reg = l_reg * alpha + ps;
; template <int KB, int DQK>
; __device__ __forceinline__ void qkt(f32x16& p0, f32x16& p1, const char* K_lds, int r32, int hi, const bf16x8* qr, const char* qrl) {
;     constexpr int SHMK = 64 * DQK * 2, NF = DQK / 16, NFR = NF > 8 ? 8 : NF;
;     p0 = f32x16{}; p1 = f32x16{};
;     const char* kb[4];
; #pragma unroll
;     for (int dd = 0; dd < 4; ++dd) kb[dd] = K_lds + KB * SHMK + kswz<DQK>(r32, (dd * 16 + hi * 8) * 2);
; #pragma unroll
;     for (int d0 = 0; d0 < NF; ++d0) { const char* a = kb[d0 & 3] + (d0 >> 2) * 128;
;         bf16x8 b0 = *reinterpret_cast<const bf16x8*>(a);
;         bf16x8 b1 = *reinterpret_cast<const bf16x8*>(a + 32 * DQK * 2);
;         bf16x8 q; if (d0 < NFR) q = qr[d0]; else q = *reinterpret_cast<const bf16x8*>(qrl + (d0 - NFR) * 1024);
;         p0 = __builtin_amdgcn_mfma_f32_32x32x16_bf16(b0, q, p0, 0, 0, 0);
;         p1 = __builtin_amdgcn_mfma_f32_32x32x16_bf16(b1, q, p1, 0, 0, 0); }
.LBB0_526:
	ds_read_b128 v[66:69], v212 offset:57344
	ds_read_b128 v[70:73], v221 offset:12288
	ds_read_b128 v[186:189], v213 offset:57344
	ds_read_b128 v[226:229], v220 offset:12288
	v_add_f32_e32 v0, 0, v150
	v_add_f32_e32 v0, v163, v0
	s_waitcnt lgkmcnt(3)
	v_mfma_f32_32x32x16_bf16 v[82:97], v[66:69], v[126:129], 0
	v_add_f32_e32 v0, v151, v0
	v_add_f32_e32 v0, v161, v0
	v_add_f32_e32 v0, v152, v0
	v_add_f32_e32 v0, v160, v0
	v_add_f32_e32 v0, v153, v0
	v_add_f32_e32 v0, v159, v0
	v_add_f32_e32 v0, v154, v0
	s_waitcnt lgkmcnt(2)
	v_mfma_f32_32x32x16_bf16 v[66:81], v[70:73], v[126:129], 0
	v_add_f32_e32 v0, v158, v0
	v_add_f32_e32 v0, v155, v0
	v_add_f32_e32 v0, v157, v0
	v_exp_f32_e32 v138, v138
	v_add_f32_e32 v0, v148, v0
	v_exp_f32_e32 v139, v139
	v_add_f32_e32 v0, v156, v0
	s_waitcnt lgkmcnt(1)
	v_mfma_f32_32x32x16_bf16 v[82:97], v[186:189], v[122:125], v[82:97]
	v_exp_f32_e32 v142, v142
	v_add_f32_e32 v0, v147, v0
	v_exp_f32_e32 v143, v143
	v_add_f32_e32 v0, v149, v0
	v_exp_f32_e32 v130, v130
	v_add_f32_e32 v0, v138, v0
	v_exp_f32_e32 v131, v131
	s_waitcnt lgkmcnt(0)
	v_mfma_f32_32x32x16_bf16 v[66:81], v[226:229], v[122:125], v[66:81]
	ds_read_b128 v[186:189], v211 offset:57344
	ds_read_b128 v[226:229], v219 offset:12288
	v_add_f32_e32 v0, v139, v0
	v_exp_f32_e32 v136, v136
	v_add_f32_e32 v0, v142, v0
	v_exp_f32_e32 v137, v137
	v_add_f32_e32 v0, v143, v0
	v_exp_f32_e32 v140, v140
	s_waitcnt lgkmcnt(1)
	v_mfma_f32_32x32x16_bf16 v[82:97], v[186:189], v[118:121], v[82:97]
	v_add_f32_e32 v0, v130, v0
	v_exp_f32_e32 v141, v141
	v_add_f32_e32 v0, v131, v0
	v_exp_f32_e32 v144, v144
	v_add_f32_e32 v0, v136, v0
	v_exp_f32_e32 v145, v145
	v_add_f32_e32 v0, v137, v0
	s_waitcnt lgkmcnt(0)
	v_mfma_f32_32x32x16_bf16 v[66:81], v[226:229], v[118:121], v[66:81]
	ds_read_b128 v[186:189], v210 offset:57344
	ds_read_b128 v[226:229], v218 offset:12288
	v_exp_f32_e32 v132, v132
	v_add_f32_e32 v0, v140, v0
	v_exp_f32_e32 v133, v133
	v_add_f32_e32 v0, v141, v0
	v_exp_f32_e32 v134, v134
	v_add_f32_e32 v0, v144, v0
	s_waitcnt lgkmcnt(1)
	v_mfma_f32_32x32x16_bf16 v[82:97], v[186:189], v[114:117], v[82:97]
	v_exp_f32_e32 v135, v135
	v_add_f32_e32 v0, v145, v0
	v_add_f32_e32 v0, v132, v0
	v_add_f32_e32 v0, v133, v0
	v_add_f32_e32 v0, v134, v0
	v_add_f32_e32 v0, v135, v0
	v_mov_b32_e32 v225, v0
	s_waitcnt lgkmcnt(0)
	v_mfma_f32_32x32x16_bf16 v[66:81], v[226:229], v[114:117], v[66:81]
	ds_read_b128 v[186:189], v212 offset:57472
	ds_read_b128 v[226:229], v221 offset:12416
	v_permlane32_swap_b32_e32 v0, v225
	s_waitcnt lgkmcnt(1)
	v_mfma_f32_32x32x16_bf16 v[82:97], v[186:189], v[102:105], v[82:97]
	s_waitcnt lgkmcnt(0)
	v_mfma_f32_32x32x16_bf16 v[66:81], v[226:229], v[102:105], v[66:81]
	ds_read_b128 v[186:189], v213 offset:57472
	ds_read_b128 v[226:229], v220 offset:12416
	s_waitcnt lgkmcnt(1)
	v_mfma_f32_32x32x16_bf16 v[82:97], v[186:189], v[98:101], v[82:97]
	s_waitcnt lgkmcnt(0)
	v_mfma_f32_32x32x16_bf16 v[66:81], v[226:229], v[98:101], v[66:81]
	ds_read_b128 v[186:189], v211 offset:57472
	ds_read_b128 v[226:229], v219 offset:12416
	s_waitcnt lgkmcnt(1)
	v_mfma_f32_32x32x16_bf16 v[82:97], v[186:189], v[110:113], v[82:97]
	s_waitcnt lgkmcnt(0)
	v_mfma_f32_32x32x16_bf16 v[66:81], v[226:229], v[110:113], v[66:81]
	ds_read_b128 v[186:189], v210 offset:57472
	ds_read_b128 v[226:229], v218 offset:12416
	s_waitcnt lgkmcnt(1)
	v_mfma_f32_32x32x16_bf16 v[82:97], v[186:189], v[106:109], v[82:97]
	s_waitcnt lgkmcnt(0)
	v_mfma_f32_32x32x16_bf16 v[66:81], v[226:229], v[106:109], v[66:81]
	ds_read_b128 v[186:189], v212 offset:57600
	ds_read_b128 v[226:229], v221 offset:12544
	ds_read_b128 v[230:233], v209
	s_waitcnt lgkmcnt(0)
	v_mfma_f32_32x32x16_bf16 v[82:97], v[186:189], v[230:233], v[82:97]
	v_mfma_f32_32x32x16_bf16 v[66:81], v[226:229], v[230:233], v[66:81]
	ds_read_b128 v[186:189], v213 offset:57600
	ds_read_b128 v[226:229], v220 offset:12544
	ds_read_b128 v[230:233], v209 offset:1024
	s_waitcnt lgkmcnt(0)
	v_mfma_f32_32x32x16_bf16 v[82:97], v[186:189], v[230:233], v[82:97]
	v_mfma_f32_32x32x16_bf16 v[66:81], v[226:229], v[230:233], v[66:81]
	ds_read_b128 v[186:189], v211 offset:57600
	ds_read_b128 v[226:229], v219 offset:12544
	ds_read_b128 v[230:233], v209 offset:2048
	s_waitcnt lgkmcnt(0)
	v_mfma_f32_32x32x16_bf16 v[82:97], v[186:189], v[230:233], v[82:97]
	v_mfma_f32_32x32x16_bf16 v[66:81], v[226:229], v[230:233], v[66:81]
	ds_read_b128 v[186:189], v210 offset:57600
	ds_read_b128 v[226:229], v218 offset:12544
	ds_read_b128 v[230:233], v209 offset:3072
	v_cvt_pk_bf16_f32 v150, v150, v163
	v_cvt_pk_bf16_f32 v151, v151, v161
	v_cvt_pk_bf16_f32 v152, v152, v160
	v_cvt_pk_bf16_f32 v153, v153, v159
	v_cvt_pk_bf16_f32 v154, v154, v158
	v_cvt_pk_bf16_f32 v155, v155, v157
	s_waitcnt lgkmcnt(0)
; template <int VB>
; __device__ __forceinline__ void pv_tile(f32x16* o, int vb0, bf16x8 pa0, bf16x8 pa1, bf16x8 pa2, bf16x8 pa3) {
;     ...
;     PV_D0(0); PV_D0(1); PV_D0(2); PV_D0(3);
	v_mfma_f32_32x32x16_bf16 v[82:97], v[186:189], v[230:233], v[82:97]
	v_cvt_pk_bf16_f32 v156, v148, v156
	v_cvt_pk_bf16_f32 v157, v147, v149
	v_cvt_pk_bf16_f32 v158, v138, v139
	v_cvt_pk_bf16_f32 v159, v142, v143
	v_cvt_pk_bf16_f32 v160, v130, v131
	v_cvt_pk_bf16_f32 v161, v136, v137
	v_permlane32_swap_b32_e32 v150, v152
	v_mfma_f32_32x32x16_bf16 v[66:81], v[226:229], v[230:233], v[66:81]
	v_cvt_pk_bf16_f32 v226, v140, v141
	v_cvt_pk_bf16_f32 v227, v144, v145
	v_cvt_pk_bf16_f32 v228, v132, v133
	v_cvt_pk_bf16_f32 v229, v134, v135
	v_permlane32_swap_b32_e32 v151, v153
	v_permlane32_swap_b32_e32 v154, v156
	v_permlane32_swap_b32_e32 v155, v157
	v_permlane32_swap_b32_e32 v158, v160
	v_permlane32_swap_b32_e32 v159, v161
	v_permlane32_swap_b32_e32 v226, v228
	v_permlane32_swap_b32_e32 v227, v229
	v_lshl_add_u64 v[190:191], s[14:15], 0, v[182:183]
	v_add_co_u32_e32 v130, vcc, s19, v190
	v_lshl_add_u64 v[186:187], s[14:15], 0, v[184:185]
	s_nop 0
	v_addc_co_u32_e32 v131, vcc, 0, v191, vcc
	v_add_co_u32_e32 v134, vcc, s31, v190
	v_lshl_add_u64 v[188:189], s[14:15], 0, v[180:181]
	s_nop 0
	v_addc_co_u32_e32 v135, vcc, 0, v191, vcc
	v_add_co_u32_e32 v138, vcc, s19, v186
	global_load_dwordx4 v[130:133], v[130:131], off offset:1024
	s_nop 0
	global_load_dwordx4 v[134:137], v[134:135], off offset:1024
	v_addc_co_u32_e32 v139, vcc, 0, v187, vcc
	v_add_co_u32_e32 v142, vcc, s31, v186
	s_nop 1
	v_addc_co_u32_e32 v143, vcc, 0, v187, vcc
	v_add_co_u32_e32 v146, vcc, s20, v188
	global_load_dwordx4 v[138:141], v[138:139], off
	s_nop 0
	global_load_dwordx4 v[142:145], v[142:143], off
	v_addc_co_u32_e32 v147, vcc, 0, v189, vcc
	global_load_dwordx4 v[146:149], v[146:147], off offset:1280
	ds_read_b64_tr_b16 v[230:231], v195 offset:0
	ds_read_b64_tr_b16 v[232:233], v195 offset:0x800
	ds_read_b64_tr_b16 v[234:235], v195 offset:0x1000
	ds_read_b64_tr_b16 v[236:237], v195 offset:0x1800
	ds_read_b64_tr_b16 v[238:239], v195 offset:0x2000
	ds_read_b64_tr_b16 v[240:241], v195 offset:0x2800
	ds_read_b64_tr_b16 v[242:243], v195 offset:0x3000
	ds_read_b64_tr_b16 v[244:245], v195 offset:0x3800
	s_waitcnt lgkmcnt(15)
	s_nop 0
	s_waitcnt lgkmcnt(6)
	v_mfma_f32_32x32x16_bf16 v[50:65], v[150:153], v[230:233], v[50:65]
	ds_read_b64_tr_b16 v[230:231], v195 offset:0x200
	ds_read_b64_tr_b16 v[232:233], v195 offset:0xa00
	s_waitcnt lgkmcnt(6)
	v_mfma_f32_32x32x16_bf16 v[50:65], v[154:157], v[234:237], v[50:65]
	ds_read_b64_tr_b16 v[234:235], v195 offset:0x1200
	ds_read_b64_tr_b16 v[236:237], v195 offset:0x1a00
	s_waitcnt lgkmcnt(6)
	v_mfma_f32_32x32x16_bf16 v[50:65], v[158:161], v[238:241], v[50:65]
	ds_read_b64_tr_b16 v[238:239], v195 offset:0x2200
	ds_read_b64_tr_b16 v[240:241], v195 offset:0x2a00
	s_waitcnt lgkmcnt(6)
	v_mfma_f32_32x32x16_bf16 v[50:65], v[226:229], v[242:245], v[50:65]
	ds_read_b64_tr_b16 v[242:243], v195 offset:0x3200
	ds_read_b64_tr_b16 v[244:245], v195 offset:0x3a00
	s_waitcnt lgkmcnt(15)
	s_waitcnt lgkmcnt(6)
	v_mfma_f32_32x32x16_bf16 v[34:49], v[150:153], v[230:233], v[34:49]
	ds_read_b64_tr_b16 v[230:231], v195 offset:0x400
	ds_read_b64_tr_b16 v[232:233], v195 offset:0xc00
	s_waitcnt lgkmcnt(6)
	v_mfma_f32_32x32x16_bf16 v[34:49], v[154:157], v[234:237], v[34:49]
	ds_read_b64_tr_b16 v[234:235], v195 offset:0x1400
	ds_read_b64_tr_b16 v[236:237], v195 offset:0x1c00
	s_waitcnt lgkmcnt(6)
	v_mfma_f32_32x32x16_bf16 v[34:49], v[158:161], v[238:241], v[34:49]
	ds_read_b64_tr_b16 v[238:239], v195 offset:0x2400
	ds_read_b64_tr_b16 v[240:241], v195 offset:0x2c00
	s_waitcnt lgkmcnt(6)
	v_mfma_f32_32x32x16_bf16 v[34:49], v[226:229], v[242:245], v[34:49]
	ds_read_b64_tr_b16 v[242:243], v195 offset:0x3400
	ds_read_b64_tr_b16 v[244:245], v195 offset:0x3c00
	s_waitcnt lgkmcnt(15)
	s_waitcnt lgkmcnt(6)
	v_mfma_f32_32x32x16_bf16 v[18:33], v[150:153], v[230:233], v[18:33]
	ds_read_b64_tr_b16 v[230:231], v195 offset:0x600
	ds_read_b64_tr_b16 v[232:233], v195 offset:0xe00
	s_waitcnt lgkmcnt(6)
	v_mfma_f32_32x32x16_bf16 v[18:33], v[154:157], v[234:237], v[18:33]
	ds_read_b64_tr_b16 v[234:235], v195 offset:0x1600
	ds_read_b64_tr_b16 v[236:237], v195 offset:0x1e00
	s_waitcnt lgkmcnt(6)
	v_mfma_f32_32x32x16_bf16 v[18:33], v[158:161], v[238:241], v[18:33]
	ds_read_b64_tr_b16 v[238:239], v195 offset:0x2600
	ds_read_b64_tr_b16 v[240:241], v195 offset:0x2e00
	s_waitcnt lgkmcnt(6)
	v_mfma_f32_32x32x16_bf16 v[18:33], v[226:229], v[242:245], v[18:33]
	ds_read_b64_tr_b16 v[242:243], v195 offset:0x3600
	ds_read_b64_tr_b16 v[244:245], v195 offset:0x3e00
	s_waitcnt lgkmcnt(15)
	s_waitcnt lgkmcnt(6)
	v_mfma_f32_32x32x16_bf16 v[2:17], v[150:153], v[230:233], v[2:17]
	s_sub_i32 s4, s18, 64
	s_cmp_le_i32 s4, s2
	s_waitcnt lgkmcnt(4)
	v_mfma_f32_32x32x16_bf16 v[2:17], v[154:157], v[234:237], v[2:17]
	s_waitcnt lgkmcnt(2)
	v_mfma_f32_32x32x16_bf16 v[2:17], v[158:161], v[238:241], v[2:17]
	s_waitcnt lgkmcnt(0)
	v_mfma_f32_32x32x16_bf16 v[2:17], v[226:229], v[242:245], v[2:17]
	s_cbranch_scc1 .LBB0_528
; __device__ __forceinline__ void mask_tile(f32x16& p0, f32x16& p1, int dq) {
;     const float NEG = -__builtin_inff();
; #pragma unroll
;     for (int r = 0; r < 16; ++r) {
;         const int c = (r & 3) + 8 * (r >> 2);
;         if (dq - c < 0) p0[r] = NEG;
;         if (dq - c - 32 < 0) p1[r] = NEG;
;     }
; }
	v_add_u32_e32 v150, 64, v224
	v_cmp_gt_i32_e64 s[96:97], 26, v150
	v_cmp_gt_i32_e32 vcc, 27, v150
	v_cmp_gt_i32_e64 s[94:95], 25, v150
	v_cmp_gt_i32_e64 s[92:93], 24, v150
	v_cndmask_b32_e32 v97, v97, v203, vcc
	s_and_b64 vcc, vcc, s[96:97]
	v_cndmask_b32_e32 v96, v96, v203, vcc
	s_and_b64 vcc, vcc, s[94:95]
	v_cmp_gt_i32_e64 s[90:91], 19, v150
	v_cndmask_b32_e32 v95, v95, v203, vcc
	s_and_b64 vcc, vcc, s[92:93]
	v_cmp_gt_i32_e64 s[88:89], 18, v150
	v_cndmask_b32_e32 v94, v94, v203, vcc
	s_and_b64 vcc, vcc, s[90:91]
	v_cmp_gt_i32_e64 s[86:87], 17, v150
	v_cndmask_b32_e32 v93, v93, v203, vcc
	s_and_b64 vcc, vcc, s[88:89]
	v_cmp_gt_i32_e64 s[84:85], 16, v150
	v_cndmask_b32_e32 v92, v92, v203, vcc
	s_and_b64 vcc, vcc, s[86:87]
	v_cmp_gt_i32_e64 s[82:83], 11, v150
	v_cndmask_b32_e32 v91, v91, v203, vcc
	s_and_b64 vcc, vcc, s[84:85]
	v_cmp_gt_i32_e64 s[80:81], 10, v150
	v_cndmask_b32_e32 v90, v90, v203, vcc
	s_and_b64 vcc, vcc, s[82:83]
	v_cmp_gt_i32_e64 s[78:79], 9, v150
	v_cndmask_b32_e32 v89, v89, v203, vcc
	s_and_b64 vcc, vcc, s[80:81]
	v_cmp_gt_i32_e64 s[76:77], 8, v150
	v_cndmask_b32_e32 v88, v88, v203, vcc
	s_and_b64 vcc, vcc, s[78:79]
	v_cmp_gt_i32_e64 s[74:75], 3, v150
	v_cndmask_b32_e32 v87, v87, v203, vcc
	s_and_b64 vcc, vcc, s[76:77]
	v_cmp_gt_i32_e64 s[8:9], 2, v150
	v_cndmask_b32_e32 v86, v86, v203, vcc
	s_and_b64 vcc, vcc, s[74:75]
	v_cmp_gt_i32_e64 s[6:7], 1, v150
	v_cndmask_b32_e32 v85, v85, v203, vcc
	s_and_b64 vcc, vcc, s[8:9]
	v_cmp_gt_i32_e64 s[4:5], 0, v150
	v_cndmask_b32_e32 v84, v84, v203, vcc
	s_and_b64 vcc, vcc, s[6:7]
	v_cndmask_b32_e32 v83, v83, v203, vcc
	s_and_b64 vcc, vcc, s[4:5]
	v_cmp_gt_i32_e64 s[70:71], 58, v150
	v_cndmask_b32_e32 v82, v82, v203, vcc
	v_cmp_gt_i32_e32 vcc, 59, v150
	v_cmp_gt_i32_e64 s[68:69], 57, v150
	v_cmp_gt_i32_e64 s[66:67], 56, v150
	v_cndmask_b32_e32 v81, v81, v203, vcc
	s_and_b64 vcc, vcc, s[70:71]
	v_cndmask_b32_e32 v80, v80, v203, vcc
	s_and_b64 vcc, vcc, s[68:69]
	v_cmp_gt_i32_e64 s[64:65], 51, v150
	v_cndmask_b32_e32 v79, v79, v203, vcc
	s_and_b64 vcc, vcc, s[66:67]
	v_cmp_gt_i32_e64 s[62:63], 50, v150
	v_cndmask_b32_e32 v78, v78, v203, vcc
	s_and_b64 vcc, vcc, s[64:65]
	v_cmp_gt_i32_e64 s[60:61], 49, v150
	v_cndmask_b32_e32 v77, v77, v203, vcc
	s_and_b64 vcc, vcc, s[62:63]
	v_cmp_gt_i32_e64 s[58:59], 48, v150
	v_cndmask_b32_e32 v76, v76, v203, vcc
	s_and_b64 vcc, vcc, s[60:61]
	v_cmp_gt_i32_e64 s[56:57], 43, v150
	v_cndmask_b32_e32 v75, v75, v203, vcc
	s_and_b64 vcc, vcc, s[58:59]
	v_cmp_gt_i32_e64 s[54:55], 42, v150
	v_cndmask_b32_e32 v74, v74, v203, vcc
	s_and_b64 vcc, vcc, s[56:57]
	v_cmp_gt_i32_e64 s[52:53], 41, v150
	v_cndmask_b32_e32 v73, v73, v203, vcc
	s_and_b64 vcc, vcc, s[54:55]
	v_cmp_gt_i32_e64 s[50:51], 40, v150
	v_cndmask_b32_e32 v72, v72, v203, vcc
	s_and_b64 vcc, vcc, s[52:53]
	v_cmp_gt_i32_e64 s[48:49], 35, v150
	v_cndmask_b32_e32 v71, v71, v203, vcc
	s_and_b64 vcc, vcc, s[50:51]
	v_cmp_gt_i32_e64 s[46:47], 34, v150
	v_cndmask_b32_e32 v70, v70, v203, vcc
	s_and_b64 vcc, vcc, s[48:49]
	v_cmp_gt_i32_e64 s[44:45], 33, v150
	v_cndmask_b32_e32 v69, v69, v203, vcc
	s_and_b64 vcc, vcc, s[46:47]
	v_cmp_gt_i32_e64 s[10:11], 32, v150
	v_cndmask_b32_e32 v68, v68, v203, vcc
	s_and_b64 vcc, vcc, s[44:45]
	v_cndmask_b32_e32 v67, v67, v203, vcc
	s_and_b64 vcc, vcc, s[10:11]
	v_cndmask_b32_e32 v66, v66, v203, vcc

; __device__ __forceinline__ void mask_tile(f32x16& p0, f32x16& p1, int dq) {
;     const float NEG = -__builtin_inff();
; #pragma unroll
;     for (int r = 0; r < 16; ++r) {
;         const int c = (r & 3) + 8 * (r >> 2);
;         if (dq - c < 0) p0[r] = NEG;
;         if (dq - c - 32 < 0) p1[r] = NEG;
;     }
; }
; template <int VB>
; __device__ __forceinline__ void pv_tile(f32x16* o, int vb0, bf16x8 pa0, bf16x8 pa1, bf16x8 pa2, bf16x8 pa3) {
;     ...
;     PV_D0(0); PV_D0(1); PV_D0(2); PV_D0(3);
.LBB0_534:
	ds_read_b64_tr_b16 v[186:187], v195 offset:0x4000
	ds_read_b64_tr_b16 v[188:189], v195 offset:0x4800
	ds_read_b64_tr_b16 v[230:231], v195 offset:0x5000
	ds_read_b64_tr_b16 v[232:233], v195 offset:0x5800
	ds_read_b64_tr_b16 v[234:235], v195 offset:0x6000
	ds_read_b64_tr_b16 v[236:237], v195 offset:0x6800
	ds_read_b64_tr_b16 v[238:239], v195 offset:0x7000
	ds_read_b64_tr_b16 v[240:241], v195 offset:0x7800
	s_waitcnt lgkmcnt(15)
	s_nop 0
	s_waitcnt lgkmcnt(6)
	v_mfma_f32_32x32x16_bf16 v[50:65], v[150:153], v[186:189], v[50:65]
	ds_read_b64_tr_b16 v[186:187], v195 offset:0x4200
	ds_read_b64_tr_b16 v[188:189], v195 offset:0x4a00
	s_waitcnt lgkmcnt(6)
	v_mfma_f32_32x32x16_bf16 v[50:65], v[154:157], v[230:233], v[50:65]
	ds_read_b64_tr_b16 v[230:231], v195 offset:0x5200
	ds_read_b64_tr_b16 v[232:233], v195 offset:0x5a00
	s_waitcnt lgkmcnt(6)
	v_mfma_f32_32x32x16_bf16 v[50:65], v[158:161], v[234:237], v[50:65]
	ds_read_b64_tr_b16 v[234:235], v195 offset:0x6200
	ds_read_b64_tr_b16 v[236:237], v195 offset:0x6a00
	s_waitcnt lgkmcnt(6)
	v_mfma_f32_32x32x16_bf16 v[50:65], v[162:165], v[238:241], v[50:65]
	ds_read_b64_tr_b16 v[238:239], v195 offset:0x7200
	ds_read_b64_tr_b16 v[240:241], v195 offset:0x7a00
	s_waitcnt lgkmcnt(15)
	s_waitcnt lgkmcnt(6)
	v_mfma_f32_32x32x16_bf16 v[34:49], v[150:153], v[186:189], v[34:49]
	ds_read_b64_tr_b16 v[186:187], v195 offset:0x4400
	ds_read_b64_tr_b16 v[188:189], v195 offset:0x4c00
	s_waitcnt lgkmcnt(6)
	v_mfma_f32_32x32x16_bf16 v[34:49], v[154:157], v[230:233], v[34:49]
	ds_read_b64_tr_b16 v[230:231], v195 offset:0x5400
	ds_read_b64_tr_b16 v[232:233], v195 offset:0x5c00
	s_waitcnt lgkmcnt(6)
	v_mfma_f32_32x32x16_bf16 v[34:49], v[158:161], v[234:237], v[34:49]
	ds_read_b64_tr_b16 v[234:235], v195 offset:0x6400
	ds_read_b64_tr_b16 v[236:237], v195 offset:0x6c00
	s_waitcnt lgkmcnt(6)
	v_mfma_f32_32x32x16_bf16 v[34:49], v[162:165], v[238:241], v[34:49]
	ds_read_b64_tr_b16 v[238:239], v195 offset:0x7400
	ds_read_b64_tr_b16 v[240:241], v195 offset:0x7c00
	s_waitcnt lgkmcnt(15)
	s_waitcnt lgkmcnt(6)
	v_mfma_f32_32x32x16_bf16 v[18:33], v[150:153], v[186:189], v[18:33]
	ds_read_b64_tr_b16 v[186:187], v195 offset:0x4600
	ds_read_b64_tr_b16 v[188:189], v195 offset:0x4e00
	s_waitcnt lgkmcnt(6)
	v_mfma_f32_32x32x16_bf16 v[18:33], v[154:157], v[230:233], v[18:33]
	ds_read_b64_tr_b16 v[230:231], v195 offset:0x5600
	ds_read_b64_tr_b16 v[232:233], v195 offset:0x5e00
	s_waitcnt lgkmcnt(6)
	v_mfma_f32_32x32x16_bf16 v[18:33], v[158:161], v[234:237], v[18:33]
	ds_read_b64_tr_b16 v[234:235], v195 offset:0x6600
	ds_read_b64_tr_b16 v[236:237], v195 offset:0x6e00
	s_waitcnt lgkmcnt(6)
	v_mfma_f32_32x32x16_bf16 v[18:33], v[162:165], v[238:241], v[18:33]
	ds_read_b64_tr_b16 v[238:239], v195 offset:0x7600
	ds_read_b64_tr_b16 v[240:241], v195 offset:0x7e00
	s_waitcnt lgkmcnt(15)
	s_waitcnt lgkmcnt(6)
	v_mfma_f32_32x32x16_bf16 v[2:17], v[150:153], v[186:189], v[2:17]
	s_cmp_le_i32 s18, s2
	s_waitcnt lgkmcnt(4)
	v_mfma_f32_32x32x16_bf16 v[2:17], v[154:157], v[230:233], v[2:17]
	s_waitcnt lgkmcnt(2)
	v_mfma_f32_32x32x16_bf16 v[2:17], v[158:161], v[234:237], v[2:17]
	s_waitcnt lgkmcnt(0)
	v_mfma_f32_32x32x16_bf16 v[2:17], v[162:165], v[238:241], v[2:17]
	s_cbranch_scc1 .LBB0_536
	v_cmp_gt_i32_e64 s[94:95], 26, v224
	v_cmp_gt_i32_e64 s[96:97], 27, v224
	v_cmp_gt_i32_e64 s[92:93], 25, v224
	s_and_b64 s[94:95], s[96:97], s[94:95]
	v_cmp_gt_i32_e64 s[90:91], 24, v224
	s_and_b64 s[92:93], s[94:95], s[92:93]
	v_cmp_gt_i32_e64 s[88:89], 19, v224
	s_and_b64 s[90:91], s[92:93], s[90:91]
	v_cmp_gt_i32_e64 s[86:87], 18, v224
	s_and_b64 s[88:89], s[90:91], s[88:89]
	v_cmp_gt_i32_e64 s[84:85], 17, v224
	s_and_b64 s[86:87], s[88:89], s[86:87]
	v_cmp_gt_i32_e64 s[82:83], 16, v224
	s_and_b64 s[84:85], s[86:87], s[84:85]
	v_cmp_gt_i32_e64 s[80:81], 11, v224
	s_and_b64 s[82:83], s[84:85], s[82:83]
	v_cmp_gt_i32_e64 s[78:79], 10, v224
	s_and_b64 s[80:81], s[82:83], s[80:81]
	v_cmp_gt_i32_e64 s[76:77], 9, v224
	s_and_b64 s[78:79], s[80:81], s[78:79]
	v_cmp_gt_i32_e64 s[74:75], 8, v224
	s_and_b64 s[76:77], s[78:79], s[76:77]
	v_cmp_gt_i32_e64 s[10:11], 3, v224
	s_and_b64 s[74:75], s[76:77], s[74:75]
	v_cmp_gt_i32_e64 s[8:9], 2, v224
	s_and_b64 s[10:11], s[74:75], s[10:11]
	v_cmp_gt_i32_e64 s[6:7], 1, v224
	s_and_b64 s[8:9], s[10:11], s[8:9]
	v_cmp_gt_i32_e64 s[4:5], 0, v224
	s_and_b64 s[6:7], s[8:9], s[6:7]
	s_and_b64 s[4:5], s[6:7], s[4:5]
	v_cmp_gt_i32_e64 s[70:71], 58, v224
	v_cndmask_b32_e64 v82, v82, v203, s[4:5]
	v_cmp_gt_i32_e64 s[4:5], 59, v224
	v_cmp_gt_i32_e64 s[68:69], 57, v224
	v_cmp_gt_i32_e64 s[66:67], 56, v224
	v_cndmask_b32_e64 v81, v81, v203, s[4:5]
	s_and_b64 s[4:5], s[4:5], s[70:71]
	v_cndmask_b32_e64 v80, v80, v203, s[4:5]
	s_and_b64 s[4:5], s[4:5], s[68:69]
	v_cmp_gt_i32_e64 s[64:65], 51, v224
	v_cndmask_b32_e64 v79, v79, v203, s[4:5]
	s_and_b64 s[4:5], s[4:5], s[66:67]
	v_cmp_gt_i32_e64 s[62:63], 50, v224
	v_cndmask_b32_e64 v78, v78, v203, s[4:5]
	s_and_b64 s[4:5], s[4:5], s[64:65]
	v_cmp_gt_i32_e64 s[60:61], 49, v224
	v_cndmask_b32_e64 v77, v77, v203, s[4:5]
	s_and_b64 s[4:5], s[4:5], s[62:63]
	v_cmp_gt_i32_e64 s[58:59], 48, v224
	v_cndmask_b32_e64 v76, v76, v203, s[4:5]
	s_and_b64 s[4:5], s[4:5], s[60:61]
	v_cmp_gt_i32_e64 s[56:57], 43, v224
	v_cndmask_b32_e64 v75, v75, v203, s[4:5]
	s_and_b64 s[4:5], s[4:5], s[58:59]
	v_cmp_gt_i32_e64 s[54:55], 42, v224
	v_cndmask_b32_e64 v74, v74, v203, s[4:5]
	s_and_b64 s[4:5], s[4:5], s[56:57]
	v_cmp_gt_i32_e64 s[52:53], 41, v224
	v_cndmask_b32_e64 v73, v73, v203, s[4:5]
	s_and_b64 s[4:5], s[4:5], s[54:55]
	v_cmp_gt_i32_e64 s[50:51], 40, v224
	v_cndmask_b32_e64 v72, v72, v203, s[4:5]
	s_and_b64 s[4:5], s[4:5], s[52:53]
	v_cmp_gt_i32_e64 s[48:49], 35, v224
	v_cndmask_b32_e64 v71, v71, v203, s[4:5]
	s_and_b64 s[4:5], s[4:5], s[50:51]
	v_cmp_gt_i32_e64 s[46:47], 34, v224
	v_cndmask_b32_e64 v70, v70, v203, s[4:5]
	s_and_b64 s[4:5], s[4:5], s[48:49]
	v_cmp_gt_i32_e64 s[44:45], 33, v224
	v_cndmask_b32_e64 v69, v69, v203, s[4:5]
	s_and_b64 s[4:5], s[4:5], s[46:47]
	v_cmp_gt_i32_e32 vcc, 32, v224
	v_cndmask_b32_e64 v68, v68, v203, s[4:5]
	s_and_b64 s[4:5], s[4:5], s[44:45]
	s_and_b64 vcc, s[4:5], vcc
	v_cndmask_b32_e64 v97, v97, v203, s[96:97]
	v_cndmask_b32_e64 v96, v96, v203, s[94:95]
	v_cndmask_b32_e64 v95, v95, v203, s[92:93]
	v_cndmask_b32_e64 v94, v94, v203, s[90:91]
	v_cndmask_b32_e64 v93, v93, v203, s[88:89]
	v_cndmask_b32_e64 v92, v92, v203, s[86:87]
	v_cndmask_b32_e64 v91, v91, v203, s[84:85]
	v_cndmask_b32_e64 v90, v90, v203, s[82:83]
	v_cndmask_b32_e64 v89, v89, v203, s[80:81]
	v_cndmask_b32_e64 v88, v88, v203, s[78:79]
	v_cndmask_b32_e64 v87, v87, v203, s[76:77]
	v_cndmask_b32_e64 v86, v86, v203, s[74:75]
	v_cndmask_b32_e64 v85, v85, v203, s[10:11]
	v_cndmask_b32_e64 v84, v84, v203, s[8:9]
	v_cndmask_b32_e64 v83, v83, v203, s[6:7]
	v_cndmask_b32_e64 v67, v67, v203, s[4:5]
	v_cndmask_b32_e32 v66, v66, v203, vcc

; __device__ __forceinline__ void finishSM(f32x16& p0, f32x16& p1, float alpha, float& l_reg, bf16x8& pa0, bf16x8& pa1, bf16x8& pa2, bf16x8& pa3) {
; #pragma unroll
;     for (int r = 0; r < 16; ++r) p1[r] = __builtin_amdgcn_exp2f(p1[r]);
;     float ps = 0;
; #pragma unroll
;     for (int r = 0; r < 16; ++r) ps += p0[r];
; #pragma unroll
;     for (int r = 0; r < 16; ++r) ps += p1[r];
;     { auto rr = __builtin_amdgcn_permlane32_swap(__float_as_uint(ps), __float_as_uint(ps), false, false);
;       ps = __uint_as_float(rr[0]) + __uint_as_float(rr[1]); }
;     l_reg = l_reg * alpha + ps;
;     ...
;     PK4(p0, 0, pa0); PK4(p0, 8, pa1); PK4(p1, 0, pa2); PK4(p1, 8, pa3);
; template <int KB, int DQK>
; __device__ __forceinline__ void qkt(f32x16& p0, f32x16& p1, const char* K_lds, int r32, int hi, const bf16x8* qr, const char* qrl) {
;     constexpr int SHMK = 64 * DQK * 2, NF = DQK / 16, NFR = NF > 8 ? 8 : NF;
;     p0 = f32x16{}; p1 = f32x16{};
;     const char* kb[4];
; #pragma unroll
;     for (int dd = 0; dd < 4; ++dd) kb[dd] = K_lds + KB * SHMK + kswz<DQK>(r32, (dd * 16 + hi * 8) * 2);
; #pragma unroll
;     for (int d0 = 0; d0 < NF; ++d0) { const char* a = kb[d0 & 3] + (d0 >> 2) * 128;
;         bf16x8 b0 = *reinterpret_cast<const bf16x8*>(a);
;         bf16x8 b1 = *reinterpret_cast<const bf16x8*>(a + 32 * DQK * 2);
;         bf16x8 q; if (d0 < NFR) q = qr[d0]; else q = *reinterpret_cast<const bf16x8*>(qrl + (d0 - NFR) * 1024);
;         p0 = __builtin_amdgcn_mfma_f32_32x32x16_bf16(b0, q, p0, 0, 0, 0);
;         p1 = __builtin_amdgcn_mfma_f32_32x32x16_bf16(b1, q, p1, 0, 0, 0); }
.LBB0_544:
	ds_read_b128 v[66:69], v212 offset:57344
	ds_read_b128 v[70:73], v221 offset:12288
	s_waitcnt lgkmcnt(1)
	v_mfma_f32_32x32x16_bf16 v[82:97], v[66:69], v[126:129], 0
	s_waitcnt lgkmcnt(0)
	v_mfma_f32_32x32x16_bf16 v[66:81], v[70:73], v[126:129], 0
	ds_read_b128 v[126:129], v213 offset:57344
	ds_read_b128 v[180:183], v220 offset:12288
	s_waitcnt lgkmcnt(1)
	v_mfma_f32_32x32x16_bf16 v[82:97], v[126:129], v[122:125], v[82:97]
	s_waitcnt lgkmcnt(0)
	v_mfma_f32_32x32x16_bf16 v[66:81], v[180:183], v[122:125], v[66:81]
	ds_read_b128 v[122:125], v211 offset:57344
	ds_read_b128 v[126:129], v219 offset:12288
	s_waitcnt lgkmcnt(1)
	v_mfma_f32_32x32x16_bf16 v[82:97], v[122:125], v[118:121], v[82:97]
	s_waitcnt lgkmcnt(0)
	v_mfma_f32_32x32x16_bf16 v[66:81], v[126:129], v[118:121], v[66:81]
	ds_read_b128 v[118:121], v210 offset:57344
	ds_read_b128 v[122:125], v218 offset:12288
	s_waitcnt lgkmcnt(1)
	v_mfma_f32_32x32x16_bf16 v[82:97], v[118:121], v[114:117], v[82:97]
	s_waitcnt lgkmcnt(0)
	v_mfma_f32_32x32x16_bf16 v[66:81], v[122:125], v[114:117], v[66:81]
	ds_read_b128 v[114:117], v212 offset:57472
	ds_read_b128 v[118:121], v221 offset:12416
	s_waitcnt lgkmcnt(1)
	v_mfma_f32_32x32x16_bf16 v[82:97], v[114:117], v[102:105], v[82:97]
	s_waitcnt lgkmcnt(0)
	v_mfma_f32_32x32x16_bf16 v[66:81], v[118:121], v[102:105], v[66:81]
	ds_read_b128 v[102:105], v213 offset:57472
	ds_read_b128 v[114:117], v220 offset:12416
	s_waitcnt lgkmcnt(1)
	v_mfma_f32_32x32x16_bf16 v[82:97], v[102:105], v[98:101], v[82:97]
	s_waitcnt lgkmcnt(0)
	v_mfma_f32_32x32x16_bf16 v[66:81], v[114:117], v[98:101], v[66:81]
	ds_read_b128 v[98:101], v211 offset:57472
	ds_read_b128 v[102:105], v219 offset:12416
	s_waitcnt lgkmcnt(1)
	v_mfma_f32_32x32x16_bf16 v[82:97], v[98:101], v[110:113], v[82:97]
	s_waitcnt lgkmcnt(0)
	v_mfma_f32_32x32x16_bf16 v[66:81], v[102:105], v[110:113], v[66:81]
	ds_read_b128 v[98:101], v210 offset:57472
	ds_read_b128 v[102:105], v218 offset:12416
	s_waitcnt lgkmcnt(1)
	v_mfma_f32_32x32x16_bf16 v[82:97], v[98:101], v[106:109], v[82:97]
	s_waitcnt lgkmcnt(0)
	v_mfma_f32_32x32x16_bf16 v[66:81], v[102:105], v[106:109], v[66:81]
	ds_read_b128 v[98:101], v212 offset:57600
	ds_read_b128 v[102:105], v221 offset:12544
	ds_read_b128 v[106:109], v209
	s_waitcnt lgkmcnt(0)
	v_mfma_f32_32x32x16_bf16 v[82:97], v[98:101], v[106:109], v[82:97]
	v_mfma_f32_32x32x16_bf16 v[66:81], v[102:105], v[106:109], v[66:81]
	ds_read_b128 v[98:101], v213 offset:57600
	ds_read_b128 v[102:105], v220 offset:12544
	ds_read_b128 v[106:109], v209 offset:1024
	s_waitcnt lgkmcnt(0)
	v_mfma_f32_32x32x16_bf16 v[82:97], v[98:101], v[106:109], v[82:97]
	v_mfma_f32_32x32x16_bf16 v[66:81], v[102:105], v[106:109], v[66:81]
	ds_read_b128 v[98:101], v211 offset:57600
	ds_read_b128 v[102:105], v219 offset:12544
	ds_read_b128 v[106:109], v209 offset:2048
	s_waitcnt lgkmcnt(0)
	v_mfma_f32_32x32x16_bf16 v[82:97], v[98:101], v[106:109], v[82:97]
	v_mfma_f32_32x32x16_bf16 v[66:81], v[102:105], v[106:109], v[66:81]
	ds_read_b128 v[98:101], v210 offset:57600
	ds_read_b128 v[102:105], v218 offset:12544
	ds_read_b128 v[106:109], v209 offset:3072
	s_waitcnt lgkmcnt(0)
	v_mfma_f32_32x32x16_bf16 v[82:97], v[98:101], v[106:109], v[82:97]
	v_mfma_f32_32x32x16_bf16 v[66:81], v[102:105], v[106:109], v[66:81]
	v_add_f32_e32 v0, 0, v150
	v_add_f32_e32 v0, v163, v0
	v_add_f32_e32 v0, v151, v0
	v_add_f32_e32 v0, v161, v0
	v_add_f32_e32 v0, v152, v0
	v_add_f32_e32 v0, v160, v0
	v_add_f32_e32 v0, v153, v0
	v_add_f32_e32 v0, v159, v0
	v_add_f32_e32 v0, v154, v0
	v_add_f32_e32 v0, v158, v0
	v_add_f32_e32 v0, v155, v0
	v_add_f32_e32 v0, v157, v0
	v_exp_f32_e32 v99, v138
	v_add_f32_e32 v0, v148, v0
	v_exp_f32_e32 v108, v139
	v_add_f32_e32 v0, v156, v0
	v_exp_f32_e32 v109, v142
	v_add_f32_e32 v0, v147, v0
	v_exp_f32_e32 v110, v143
	v_add_f32_e32 v0, v149, v0
	v_exp_f32_e32 v111, v130
	v_add_f32_e32 v0, v99, v0
	v_exp_f32_e32 v112, v131
	v_add_f32_e32 v0, v108, v0
	v_exp_f32_e32 v113, v136
	v_add_f32_e32 v0, v109, v0
	v_exp_f32_e32 v114, v137
	v_add_f32_e32 v0, v110, v0
	v_exp_f32_e32 v115, v140
	v_add_f32_e32 v0, v111, v0
	v_exp_f32_e32 v116, v141
	v_add_f32_e32 v0, v112, v0
	v_exp_f32_e32 v117, v144
	v_add_f32_e32 v0, v113, v0
	v_exp_f32_e32 v118, v145
	v_add_f32_e32 v0, v114, v0
	v_exp_f32_e32 v119, v132
	v_add_f32_e32 v0, v115, v0
	v_exp_f32_e32 v120, v133
	v_add_f32_e32 v0, v116, v0
	v_exp_f32_e32 v121, v134
	v_add_f32_e32 v0, v117, v0
	v_exp_f32_e32 v122, v135
	v_add_f32_e32 v0, v118, v0
	v_add_f32_e32 v0, v119, v0
	v_add_f32_e32 v0, v120, v0
	v_add_f32_e32 v0, v121, v0
	v_add_f32_e32 v0, v122, v0
	v_mov_b32_e32 v98, v0
	s_nop 1
	v_permlane32_swap_b32_e32 v0, v98
	v_cvt_pk_bf16_f32 v100, v150, v163
	v_cvt_pk_bf16_f32 v101, v151, v161
	v_cvt_pk_bf16_f32 v102, v152, v160
	v_cvt_pk_bf16_f32 v103, v153, v159
	v_cvt_pk_bf16_f32 v104, v154, v158
	v_cvt_pk_bf16_f32 v105, v155, v157
	v_cvt_pk_bf16_f32 v106, v148, v156
	v_cvt_pk_bf16_f32 v107, v147, v149
	v_cvt_pk_bf16_f32 v108, v99, v108
	v_cvt_pk_bf16_f32 v109, v109, v110
	v_cvt_pk_bf16_f32 v110, v111, v112
	v_cvt_pk_bf16_f32 v111, v113, v114
	v_cvt_pk_bf16_f32 v112, v115, v116
	v_cvt_pk_bf16_f32 v113, v117, v118
	v_cvt_pk_bf16_f32 v114, v119, v120
	v_cvt_pk_bf16_f32 v115, v121, v122
	s_nop 0
	v_permlane32_swap_b32_e32 v100, v102
	v_permlane32_swap_b32_e32 v101, v103
	v_permlane32_swap_b32_e32 v104, v106
	v_permlane32_swap_b32_e32 v105, v107
	v_permlane32_swap_b32_e32 v108, v110
	v_permlane32_swap_b32_e32 v109, v111
	v_permlane32_swap_b32_e32 v112, v114
	v_permlane32_swap_b32_e32 v113, v115
	ds_read_b64_tr_b16 v[116:117], v195 offset:0
	ds_read_b64_tr_b16 v[118:119], v195 offset:0x800
	ds_read_b64_tr_b16 v[120:121], v195 offset:0x1000
	ds_read_b64_tr_b16 v[122:123], v195 offset:0x1800
	ds_read_b64_tr_b16 v[124:125], v195 offset:0x2000
	ds_read_b64_tr_b16 v[126:127], v195 offset:0x2800
	ds_read_b64_tr_b16 v[128:129], v195 offset:0x3000
	ds_read_b64_tr_b16 v[130:131], v195 offset:0x3800
	s_waitcnt lgkmcnt(15)
; __device__ __forceinline__ void mask_tile(f32x16& p0, f32x16& p1, int dq) {
;     const float NEG = -__builtin_inff();
; #pragma unroll
;     for (int r = 0; r < 16; ++r) {
;         const int c = (r & 3) + 8 * (r >> 2);
;         if (dq - c < 0) p0[r] = NEG;
;         if (dq - c - 32 < 0) p1[r] = NEG;
;     }
; }
; template <int VB>
; __device__ __forceinline__ void pv_tile(f32x16* o, int vb0, bf16x8 pa0, bf16x8 pa1, bf16x8 pa2, bf16x8 pa3) {
;     ...
;     PV_D0(0); PV_D0(1); PV_D0(2); PV_D0(3);
	s_nop 0
	s_waitcnt lgkmcnt(6)
	v_mfma_f32_32x32x16_bf16 v[50:65], v[100:103], v[116:119], v[50:65]
	ds_read_b64_tr_b16 v[116:117], v195 offset:0x200
	ds_read_b64_tr_b16 v[118:119], v195 offset:0xa00
	s_waitcnt lgkmcnt(6)
	v_mfma_f32_32x32x16_bf16 v[50:65], v[104:107], v[120:123], v[50:65]
	ds_read_b64_tr_b16 v[120:121], v195 offset:0x1200
	ds_read_b64_tr_b16 v[122:123], v195 offset:0x1a00
	s_waitcnt lgkmcnt(6)
	v_mfma_f32_32x32x16_bf16 v[50:65], v[108:111], v[124:127], v[50:65]
	ds_read_b64_tr_b16 v[124:125], v195 offset:0x2200
	ds_read_b64_tr_b16 v[126:127], v195 offset:0x2a00
	s_waitcnt lgkmcnt(6)
	v_mfma_f32_32x32x16_bf16 v[50:65], v[112:115], v[128:131], v[50:65]
	ds_read_b64_tr_b16 v[128:129], v195 offset:0x3200
	ds_read_b64_tr_b16 v[130:131], v195 offset:0x3a00
	s_waitcnt lgkmcnt(15)
	s_waitcnt lgkmcnt(6)
	v_mfma_f32_32x32x16_bf16 v[34:49], v[100:103], v[116:119], v[34:49]
	ds_read_b64_tr_b16 v[116:117], v195 offset:0x400
	ds_read_b64_tr_b16 v[118:119], v195 offset:0xc00
	s_waitcnt lgkmcnt(6)
	v_mfma_f32_32x32x16_bf16 v[34:49], v[104:107], v[120:123], v[34:49]
	ds_read_b64_tr_b16 v[120:121], v195 offset:0x1400
	ds_read_b64_tr_b16 v[122:123], v195 offset:0x1c00
	s_waitcnt lgkmcnt(6)
	v_mfma_f32_32x32x16_bf16 v[34:49], v[108:111], v[124:127], v[34:49]
	ds_read_b64_tr_b16 v[124:125], v195 offset:0x2400
	ds_read_b64_tr_b16 v[126:127], v195 offset:0x2c00
	s_waitcnt lgkmcnt(6)
	v_mfma_f32_32x32x16_bf16 v[34:49], v[112:115], v[128:131], v[34:49]
	ds_read_b64_tr_b16 v[128:129], v195 offset:0x3400
	ds_read_b64_tr_b16 v[130:131], v195 offset:0x3c00
	s_waitcnt lgkmcnt(15)
	s_waitcnt lgkmcnt(6)
	v_mfma_f32_32x32x16_bf16 v[18:33], v[100:103], v[116:119], v[18:33]
	ds_read_b64_tr_b16 v[116:117], v195 offset:0x600
	ds_read_b64_tr_b16 v[118:119], v195 offset:0xe00
	s_waitcnt lgkmcnt(6)
	v_mfma_f32_32x32x16_bf16 v[18:33], v[104:107], v[120:123], v[18:33]
	ds_read_b64_tr_b16 v[120:121], v195 offset:0x1600
	ds_read_b64_tr_b16 v[122:123], v195 offset:0x1e00
	s_waitcnt lgkmcnt(6)
	v_mfma_f32_32x32x16_bf16 v[18:33], v[108:111], v[124:127], v[18:33]
	ds_read_b64_tr_b16 v[124:125], v195 offset:0x2600
	ds_read_b64_tr_b16 v[126:127], v195 offset:0x2e00
	s_waitcnt lgkmcnt(6)
	v_mfma_f32_32x32x16_bf16 v[18:33], v[112:115], v[128:131], v[18:33]
	ds_read_b64_tr_b16 v[128:129], v195 offset:0x3600
	ds_read_b64_tr_b16 v[130:131], v195 offset:0x3e00
	s_waitcnt lgkmcnt(15)
	s_waitcnt lgkmcnt(6)
	v_mfma_f32_32x32x16_bf16 v[2:17], v[100:103], v[116:119], v[2:17]
	s_cmp_lt_i32 s41, 8
	s_waitcnt lgkmcnt(4)
	v_mfma_f32_32x32x16_bf16 v[2:17], v[104:107], v[120:123], v[2:17]
	s_waitcnt lgkmcnt(2)
	v_mfma_f32_32x32x16_bf16 v[2:17], v[108:111], v[124:127], v[2:17]
	s_waitcnt lgkmcnt(0)
	v_mfma_f32_32x32x16_bf16 v[2:17], v[112:115], v[128:131], v[2:17]
	s_cbranch_scc0 .LBB0_546
	v_subrev_u32_e32 v99, s72, v208
	v_add_u32_e32 v99, 64, v99
	v_cmp_gt_i32_e64 s[94:95], 26, v99
	v_cmp_gt_i32_e64 s[96:97], 27, v99
	v_cmp_gt_i32_e64 s[92:93], 25, v99
	s_and_b64 s[94:95], s[96:97], s[94:95]
	v_cmp_gt_i32_e64 s[90:91], 24, v99
	s_and_b64 s[92:93], s[94:95], s[92:93]
	v_cmp_gt_i32_e64 s[88:89], 19, v99
	s_and_b64 s[90:91], s[92:93], s[90:91]
	v_cmp_gt_i32_e64 s[86:87], 18, v99
	s_and_b64 s[88:89], s[90:91], s[88:89]
	v_cmp_gt_i32_e64 s[84:85], 17, v99
	s_and_b64 s[86:87], s[88:89], s[86:87]
	v_cmp_gt_i32_e64 s[82:83], 16, v99
	s_and_b64 s[84:85], s[86:87], s[84:85]
	v_cmp_gt_i32_e64 s[80:81], 11, v99
	s_and_b64 s[82:83], s[84:85], s[82:83]
	v_cmp_gt_i32_e64 s[78:79], 10, v99
	s_and_b64 s[80:81], s[82:83], s[80:81]
	v_cmp_gt_i32_e64 s[76:77], 9, v99
	s_and_b64 s[78:79], s[80:81], s[78:79]
	v_cmp_gt_i32_e64 s[74:75], 8, v99
	s_and_b64 s[76:77], s[78:79], s[76:77]
	v_cmp_gt_i32_e64 s[10:11], 3, v99
	s_and_b64 s[74:75], s[76:77], s[74:75]
	v_cmp_gt_i32_e64 s[8:9], 2, v99
	s_and_b64 s[10:11], s[74:75], s[10:11]
	v_cmp_gt_i32_e64 s[6:7], 1, v99
	s_and_b64 s[8:9], s[10:11], s[8:9]
	v_cmp_gt_i32_e64 s[4:5], 0, v99
	s_and_b64 s[6:7], s[8:9], s[6:7]
	s_and_b64 s[4:5], s[6:7], s[4:5]
	v_cmp_gt_i32_e64 s[70:71], 58, v99
	v_cndmask_b32_e64 v82, v82, v203, s[4:5]
	v_cmp_gt_i32_e64 s[4:5], 59, v99
	v_cmp_gt_i32_e64 s[68:69], 57, v99
	v_cmp_gt_i32_e64 s[66:67], 56, v99
	v_cndmask_b32_e64 v81, v81, v203, s[4:5]
	s_and_b64 s[4:5], s[4:5], s[70:71]
	v_cndmask_b32_e64 v80, v80, v203, s[4:5]
	s_and_b64 s[4:5], s[4:5], s[68:69]
	v_cmp_gt_i32_e64 s[64:65], 51, v99
	v_cndmask_b32_e64 v79, v79, v203, s[4:5]
	s_and_b64 s[4:5], s[4:5], s[66:67]
	v_cmp_gt_i32_e64 s[62:63], 50, v99
	v_cndmask_b32_e64 v78, v78, v203, s[4:5]
	s_and_b64 s[4:5], s[4:5], s[64:65]
	v_cmp_gt_i32_e64 s[60:61], 49, v99
	v_cndmask_b32_e64 v77, v77, v203, s[4:5]
	s_and_b64 s[4:5], s[4:5], s[62:63]
	v_cmp_gt_i32_e64 s[58:59], 48, v99
	v_cndmask_b32_e64 v76, v76, v203, s[4:5]
	s_and_b64 s[4:5], s[4:5], s[60:61]
	v_cmp_gt_i32_e64 s[56:57], 43, v99
	v_cndmask_b32_e64 v75, v75, v203, s[4:5]
	s_and_b64 s[4:5], s[4:5], s[58:59]
	v_cmp_gt_i32_e64 s[54:55], 42, v99
	v_cndmask_b32_e64 v74, v74, v203, s[4:5]
	s_and_b64 s[4:5], s[4:5], s[56:57]
	v_cmp_gt_i32_e64 s[52:53], 41, v99
	v_cndmask_b32_e64 v73, v73, v203, s[4:5]
	s_and_b64 s[4:5], s[4:5], s[54:55]
	v_cmp_gt_i32_e64 s[50:51], 40, v99
	v_cndmask_b32_e64 v72, v72, v203, s[4:5]
	s_and_b64 s[4:5], s[4:5], s[52:53]
	v_cmp_gt_i32_e64 s[48:49], 35, v99
	v_cndmask_b32_e64 v71, v71, v203, s[4:5]
	s_and_b64 s[4:5], s[4:5], s[50:51]
	v_cmp_gt_i32_e64 s[46:47], 34, v99
	v_cndmask_b32_e64 v70, v70, v203, s[4:5]
	s_and_b64 s[4:5], s[4:5], s[48:49]
	v_cmp_gt_i32_e64 s[44:45], 33, v99
	v_cndmask_b32_e64 v69, v69, v203, s[4:5]
	s_and_b64 s[4:5], s[4:5], s[46:47]
	v_cmp_gt_i32_e32 vcc, 32, v99
	v_cndmask_b32_e64 v68, v68, v203, s[4:5]
	s_and_b64 s[4:5], s[4:5], s[44:45]
	s_and_b64 vcc, s[4:5], vcc
	v_cndmask_b32_e64 v97, v97, v203, s[96:97]
	v_cndmask_b32_e64 v96, v96, v203, s[94:95]
	v_cndmask_b32_e64 v95, v95, v203, s[92:93]
	v_cndmask_b32_e64 v94, v94, v203, s[90:91]
	v_cndmask_b32_e64 v93, v93, v203, s[88:89]
	v_cndmask_b32_e64 v92, v92, v203, s[86:87]
	v_cndmask_b32_e64 v91, v91, v203, s[84:85]
	v_cndmask_b32_e64 v90, v90, v203, s[82:83]
	v_cndmask_b32_e64 v89, v89, v203, s[80:81]
	v_cndmask_b32_e64 v88, v88, v203, s[78:79]
	v_cndmask_b32_e64 v87, v87, v203, s[76:77]
	v_cndmask_b32_e64 v86, v86, v203, s[74:75]
	v_cndmask_b32_e64 v85, v85, v203, s[10:11]
	v_cndmask_b32_e64 v84, v84, v203, s[8:9]
	v_cndmask_b32_e64 v83, v83, v203, s[6:7]
	v_cndmask_b32_e64 v67, v67, v203, s[4:5]
	v_cndmask_b32_e32 v66, v66, v203, vcc

; __device__ __forceinline__ void partialSM(f32x16& p0, f32x16& p1, float& m_reg, float& mn, float& alpha) {
;     ...
;     for (int r = 0; r < 16; ++r) p0[r] = p0[r] - mn;
; #pragma unroll
;     for (int r = 0; r < 16; ++r) p1[r] = p1[r] - mn;
; #pragma unroll
;     for (int r = 0; r < 16; ++r) p0[r] = __builtin_amdgcn_exp2f(p0[r]);
; }
; __device__ __forceinline__ void finishSM(f32x16& p0, f32x16& p1, float alpha, float& l_reg, bf16x8& pa0, bf16x8& pa1, bf16x8& pa2, bf16x8& pa3) {
; #pragma unroll
;     for (int r = 0; r < 16; ++r) p1[r] = __builtin_amdgcn_exp2f(p1[r]);
;     float ps = 0;
; #pragma unroll
;     for (int r = 0; r < 16; ++r) ps += p0[r];
; #pragma unroll
;     for (int r = 0; r < 16; ++r) ps += p1[r];
;     { auto rr = __builtin_amdgcn_permlane32_swap(__float_as_uint(ps), __float_as_uint(ps), false, false);
;       ps = __uint_as_float(rr[0]) + __uint_as_float(rr[1]); }
;     l_reg = l_reg * alpha + ps;
;     ...
;     PK4(p0, 0, pa0); PK4(p0, 8, pa1); PK4(p1, 0, pa2); PK4(p1, 8, pa3);
; template <int VB>
; __device__ __forceinline__ void pv_tile(f32x16* o, int vb0, bf16x8 pa0, bf16x8 pa1, bf16x8 pa2, bf16x8 pa3) {
;     ...
;     PV_D0(0); PV_D0(1); PV_D0(2); PV_D0(3);
.LBB0_550:
	v_cndmask_b32_e64 v100, v100, v162, s[44:45]
	v_sub_f32_e32 v82, v82, v100
	v_sub_f32_e32 v83, v83, v100
	v_exp_f32_e32 v82, v82
	v_sub_f32_e32 v84, v84, v100
	v_exp_f32_e32 v83, v83
	v_sub_f32_e32 v85, v85, v100
	v_exp_f32_e32 v84, v84
	v_sub_f32_e32 v86, v86, v100
	v_sub_f32_e32 v66, v66, v100
	v_exp_f32_e32 v85, v85
	v_sub_f32_e32 v87, v87, v100
	v_sub_f32_e32 v88, v88, v100
	v_sub_f32_e32 v89, v89, v100
	v_sub_f32_e32 v90, v90, v100
	v_sub_f32_e32 v91, v91, v100
	v_sub_f32_e32 v92, v92, v100
	v_sub_f32_e32 v93, v93, v100
	v_sub_f32_e32 v94, v94, v100
	v_sub_f32_e32 v95, v95, v100
	v_sub_f32_e32 v96, v96, v100
	v_sub_f32_e32 v97, v97, v100
	v_sub_f32_e32 v67, v67, v100
	v_sub_f32_e32 v68, v68, v100
	v_sub_f32_e32 v69, v69, v100
	v_sub_f32_e32 v70, v70, v100
	v_sub_f32_e32 v71, v71, v100
	v_sub_f32_e32 v72, v72, v100
	v_sub_f32_e32 v73, v73, v100
	v_sub_f32_e32 v74, v74, v100
	v_sub_f32_e32 v75, v75, v100
	v_sub_f32_e32 v76, v76, v100
	v_sub_f32_e32 v77, v77, v100
	v_sub_f32_e32 v78, v78, v100
	v_sub_f32_e32 v79, v79, v100
	v_sub_f32_e32 v80, v80, v100
	v_sub_f32_e32 v81, v81, v100
	v_exp_f32_e32 v86, v86
	v_exp_f32_e32 v100, v66
	v_add_f32_e32 v66, 0, v82
	v_exp_f32_e32 v87, v87
	v_add_f32_e32 v66, v83, v66
	v_exp_f32_e32 v88, v88
	v_add_f32_e32 v66, v84, v66
	v_exp_f32_e32 v89, v89
	v_add_f32_e32 v66, v85, v66
	v_exp_f32_e32 v90, v90
	v_add_f32_e32 v66, v86, v66
	v_exp_f32_e32 v91, v91
	v_add_f32_e32 v66, v87, v66
	v_exp_f32_e32 v92, v92
	v_add_f32_e32 v66, v88, v66
	v_exp_f32_e32 v93, v93
	v_add_f32_e32 v66, v89, v66
	v_exp_f32_e32 v94, v94
	v_add_f32_e32 v66, v90, v66
	v_exp_f32_e32 v95, v95
	v_add_f32_e32 v66, v91, v66
	v_exp_f32_e32 v96, v96
	v_add_f32_e32 v66, v92, v66
	v_exp_f32_e32 v97, v97
	v_add_f32_e32 v66, v93, v66
	v_add_f32_e32 v66, v94, v66
	v_exp_f32_e32 v101, v67
	v_add_f32_e32 v66, v95, v66
	v_exp_f32_e32 v102, v68
	v_add_f32_e32 v66, v96, v66
	v_exp_f32_e32 v103, v69
	v_add_f32_e32 v66, v97, v66
	v_exp_f32_e32 v104, v70
	v_add_f32_e32 v66, v100, v66
	v_exp_f32_e32 v105, v71
	v_add_f32_e32 v66, v101, v66
	v_exp_f32_e32 v106, v72
	v_add_f32_e32 v66, v102, v66
	v_exp_f32_e32 v107, v73
	v_add_f32_e32 v66, v103, v66
	v_exp_f32_e32 v108, v74
	v_add_f32_e32 v66, v104, v66
	v_exp_f32_e32 v109, v75
	v_add_f32_e32 v66, v105, v66
	v_exp_f32_e32 v110, v76
	v_add_f32_e32 v66, v106, v66
	v_exp_f32_e32 v111, v77
	v_add_f32_e32 v66, v107, v66
	v_exp_f32_e32 v112, v78
	v_add_f32_e32 v66, v108, v66
	v_exp_f32_e32 v113, v79
	v_add_f32_e32 v66, v109, v66
	v_exp_f32_e32 v114, v80
	v_add_f32_e32 v66, v110, v66
	v_exp_f32_e32 v115, v81
	v_add_f32_e32 v66, v111, v66
	v_add_f32_e32 v66, v112, v66
	v_add_f32_e32 v66, v113, v66
	v_add_f32_e32 v66, v114, v66
	v_add_f32_e32 v66, v115, v66
	v_mov_b32_e32 v67, v66
	s_nop 1
	v_permlane32_swap_b32_e32 v66, v67
	v_cvt_pk_bf16_f32 v68, v82, v83
	v_cvt_pk_bf16_f32 v69, v84, v85
	v_cvt_pk_bf16_f32 v70, v86, v87
	v_cvt_pk_bf16_f32 v71, v88, v89
	v_cvt_pk_bf16_f32 v72, v90, v91
	v_cvt_pk_bf16_f32 v73, v92, v93
	v_cvt_pk_bf16_f32 v74, v94, v95
	v_cvt_pk_bf16_f32 v75, v96, v97
	v_cvt_pk_bf16_f32 v76, v100, v101
	v_cvt_pk_bf16_f32 v77, v102, v103
	v_cvt_pk_bf16_f32 v78, v104, v105
	v_cvt_pk_bf16_f32 v79, v106, v107
	v_cvt_pk_bf16_f32 v80, v108, v109
	v_cvt_pk_bf16_f32 v81, v110, v111
	v_cvt_pk_bf16_f32 v82, v112, v113
	v_cvt_pk_bf16_f32 v83, v114, v115
	s_nop 0
	v_permlane32_swap_b32_e32 v68, v70
	v_permlane32_swap_b32_e32 v69, v71
	v_permlane32_swap_b32_e32 v72, v74
	v_permlane32_swap_b32_e32 v73, v75
	v_permlane32_swap_b32_e32 v76, v78
	v_permlane32_swap_b32_e32 v77, v79
	v_permlane32_swap_b32_e32 v80, v82
	v_permlane32_swap_b32_e32 v81, v83
	ds_read_b64_tr_b16 v[84:85], v195 offset:0x4000
	ds_read_b64_tr_b16 v[86:87], v195 offset:0x4800
	ds_read_b64_tr_b16 v[88:89], v195 offset:0x5000
	ds_read_b64_tr_b16 v[90:91], v195 offset:0x5800
	ds_read_b64_tr_b16 v[92:93], v195 offset:0x6000
	ds_read_b64_tr_b16 v[94:95], v195 offset:0x6800
	ds_read_b64_tr_b16 v[100:101], v195 offset:0x7000
	ds_read_b64_tr_b16 v[102:103], v195 offset:0x7800
	s_waitcnt lgkmcnt(15)
	s_nop 0
	s_waitcnt lgkmcnt(6)
	v_mfma_f32_32x32x16_bf16 v[50:65], v[68:71], v[84:87], v[50:65]
	ds_read_b64_tr_b16 v[84:85], v195 offset:0x4200
	ds_read_b64_tr_b16 v[86:87], v195 offset:0x4a00
	s_waitcnt lgkmcnt(6)
	v_mfma_f32_32x32x16_bf16 v[50:65], v[72:75], v[88:91], v[50:65]
	ds_read_b64_tr_b16 v[88:89], v195 offset:0x5200
	ds_read_b64_tr_b16 v[90:91], v195 offset:0x5a00
	s_waitcnt lgkmcnt(6)
	v_mfma_f32_32x32x16_bf16 v[50:65], v[76:79], v[92:95], v[50:65]
	ds_read_b64_tr_b16 v[92:93], v195 offset:0x6200
	ds_read_b64_tr_b16 v[94:95], v195 offset:0x6a00
	s_waitcnt lgkmcnt(6)
	v_mfma_f32_32x32x16_bf16 v[50:65], v[80:83], v[100:103], v[50:65]
	ds_read_b64_tr_b16 v[100:101], v195 offset:0x7200
	ds_read_b64_tr_b16 v[102:103], v195 offset:0x7a00
	s_waitcnt lgkmcnt(15)
	s_waitcnt lgkmcnt(6)
	v_mfma_f32_32x32x16_bf16 v[34:49], v[68:71], v[84:87], v[34:49]
	ds_read_b64_tr_b16 v[84:85], v195 offset:0x4400
	ds_read_b64_tr_b16 v[86:87], v195 offset:0x4c00
	s_waitcnt lgkmcnt(6)
	v_mfma_f32_32x32x16_bf16 v[34:49], v[72:75], v[88:91], v[34:49]
	ds_read_b64_tr_b16 v[88:89], v195 offset:0x5400
	ds_read_b64_tr_b16 v[90:91], v195 offset:0x5c00
	s_waitcnt lgkmcnt(6)
	v_mfma_f32_32x32x16_bf16 v[34:49], v[76:79], v[92:95], v[34:49]
	ds_read_b64_tr_b16 v[92:93], v195 offset:0x6400
	ds_read_b64_tr_b16 v[94:95], v195 offset:0x6c00
	s_waitcnt lgkmcnt(6)
	v_mfma_f32_32x32x16_bf16 v[34:49], v[80:83], v[100:103], v[34:49]
	ds_read_b64_tr_b16 v[100:101], v195 offset:0x7400
	ds_read_b64_tr_b16 v[102:103], v195 offset:0x7c00
	s_waitcnt lgkmcnt(15)
	s_waitcnt lgkmcnt(6)
	v_mfma_f32_32x32x16_bf16 v[18:33], v[68:71], v[84:87], v[18:33]
	ds_read_b64_tr_b16 v[84:85], v195 offset:0x4600
	ds_read_b64_tr_b16 v[86:87], v195 offset:0x4e00
	s_waitcnt lgkmcnt(6)
	v_mfma_f32_32x32x16_bf16 v[18:33], v[72:75], v[88:91], v[18:33]
	ds_read_b64_tr_b16 v[88:89], v195 offset:0x5600
	ds_read_b64_tr_b16 v[90:91], v195 offset:0x5e00
	s_waitcnt lgkmcnt(6)
	v_mfma_f32_32x32x16_bf16 v[18:33], v[76:79], v[92:95], v[18:33]
	ds_read_b64_tr_b16 v[92:93], v195 offset:0x6600
	ds_read_b64_tr_b16 v[94:95], v195 offset:0x6e00
	s_waitcnt lgkmcnt(6)
	v_mfma_f32_32x32x16_bf16 v[18:33], v[80:83], v[100:103], v[18:33]
	ds_read_b64_tr_b16 v[100:101], v195 offset:0x7600
	ds_read_b64_tr_b16 v[102:103], v195 offset:0x7e00
	s_waitcnt lgkmcnt(15)
	s_waitcnt lgkmcnt(6)
	v_mfma_f32_32x32x16_bf16 v[2:17], v[68:71], v[84:87], v[2:17]
	s_waitcnt lgkmcnt(4)
	v_mfma_f32_32x32x16_bf16 v[2:17], v[72:75], v[88:91], v[2:17]
	s_waitcnt lgkmcnt(2)
	v_mfma_f32_32x32x16_bf16 v[2:17], v[76:79], v[92:95], v[2:17]
	s_waitcnt lgkmcnt(0)
	v_mfma_f32_32x32x16_bf16 v[2:17], v[80:83], v[100:103], v[2:17]
	s_barrier
; __device__ __forceinline__ float lane_xor1(float v) { return __builtin_bit_cast(float, __builtin_amdgcn_update_dpp(0, __builtin_bit_cast(int, v), 0xB1, 0xF, 0xF, false)); }
; __device__ __forceinline__ int crow(int r, int hi) { return (r & 3) + 8 * (r >> 2) + 4 * hi; }
; __device__ __forceinline__ unsigned cvtpk(float lo, float hi) { unsigned r; asm volatile("v_cvt_pk_bf16_f32 %0, %1, %2" : "=v"(r) : "v"(lo), "v"(hi)); return r; }
; template <bool MLA, int MODE, bool PIPE>
; __device__ __forceinline__ void attn_block(const AttnArgs& a, char* lds) {
;     ...
;     if (hi == 0) li_l[r32] = l_reg; asm volatile("s_waitcnt lgkmcnt(0)" ::: "memory");
;     float rli[16];
; #pragma unroll
;     for (int r = 0; r < 16; ++r) rli[r] = __builtin_amdgcn_rcpf(li_l[crow(r, hi)]);
;     if constexpr (MODE == 0) {
;         bf16_t* Ow = a.Out + (size_t)qlo * 1024;
; #pragma unroll
;         for (int r = 0; r < 16; ++r) { const int orow = crow(r, hi);
; #pragma unroll
;             for (int d0 = 0; d0 < 4; ++d0) { const float v = o[d0][r] * rli[r]; const float vn = lane_xor1(v);
;                 if ((r32 & 1) == 0) *(unsigned*)(Ow + (size_t)orow * 1024 + d0 * 32 + r32) = cvtpk(v, vn); } }
	s_and_saveexec_b64 s[4:5], s[42:43]
	v_add_f32_e32 v0, v0, v98
	v_fmac_f32_e32 v0, v207, v146
	v_add_f32_e32 v66, v66, v67
	v_fmac_f32_e32 v66, v0, v99
	ds_write_b32 v197, v66
	s_or_b64 exec, exec, s[4:5]
	v_readlane_b32 s4, v254, 53
	s_add_u32 s3, s14, s24
	v_readlane_b32 s5, v254, 54
	s_addc_u32 s6, s15, s25
	s_lshl_b64 s[4:5], s[4:5], 1
	s_waitcnt lgkmcnt(0)
	s_add_u32 s3, s3, s4
	ds_read_b128 v[78:81], v196
	ds_read_b128 v[74:77], v196 offset:32
	s_addc_u32 s4, s6, s5
	v_readlane_b32 s5, v254, 55
	s_lshl_b32 s5, s5, 1
	s_add_u32 s5, s3, s5
	s_addc_u32 s4, s4, 0
	s_ashr_i32 s3, s2, 31
	s_waitcnt lgkmcnt(1)
	v_rcp_f32_e32 v78, v78
	s_lshl_b64 s[2:3], s[2:3], 11
	ds_read_b128 v[70:73], v196 offset:64
	ds_read_b128 v[66:69], v196 offset:96
	s_add_u32 s2, s5, s2
	v_and_b32_e32 v0, 1, v193
	s_addc_u32 s3, s4, s3
	v_cmp_eq_u32_e64 s[42:43], 0, v0
	v_lshlrev_b32_e32 v0, 1, v194
	v_lshl_add_u64 v[82:83], s[2:3], 0, v[0:1]
	v_lshlrev_b32_e32 v0, 13, v192
	v_lshl_add_u64 v[82:83], v[82:83], 0, v[0:1]
	s_mov_b64 s[2:3], 0x20c00000
	v_mul_f32_e32 v0, v50, v78
	v_mov_b32_e32 v50, v1
	v_lshl_add_u64 v[82:83], v[82:83], 0, s[2:3]
	s_nop 0
	v_mov_b32_dpp v50, v0 quad_perm:[1,0,3,2] row_mask:0xf bank_mask:0xf
	s_and_saveexec_b64 s[2:3], s[42:43]
	s_cbranch_execz .LBB0_554
	v_cvt_pk_bf16_f32 v0, v0, v50
	global_store_dword v[82:83], v0, off

; __device__ __forceinline__ void finishSM(f32x16& p0, f32x16& p1, float alpha, float& l_reg, bf16x8& pa0, bf16x8& pa1, bf16x8& pa2, bf16x8& pa3) {
; #pragma unroll
;     for (int r = 0; r < 16; ++r) p1[r] = __builtin_amdgcn_exp2f(p1[r]);
;     float ps = 0;
; #pragma unroll
;     for (int r = 0; r < 16; ++r) ps += p0[r];
; #pragma unroll
;     for (int r = 0; r < 16; ++r) ps += p1[r];
;     { auto rr = __builtin_amdgcn_permlane32_swap(__float_as_uint(ps), __float_as_uint(ps), false, false);
;       ps = __uint_as_float(rr[0]) + __uint_as_float(rr[1]); }
;     l_reg = l_reg * alpha + ps;
;     ...
;     PK4(p0, 0, pa0); PK4(p0, 8, pa1); PK4(p1, 0, pa2); PK4(p1, 8, pa3);
; template <int KB, int DQK>
; __device__ __forceinline__ void qkt(f32x16& p0, f32x16& p1, const char* K_lds, int r32, int hi, const bf16x8* qr, const char* qrl) {
;     constexpr int SHMK = 64 * DQK * 2, NF = DQK / 16, NFR = NF > 8 ? 8 : NF;
;     p0 = f32x16{}; p1 = f32x16{};
;     const char* kb[4];
; #pragma unroll
;     for (int dd = 0; dd < 4; ++dd) kb[dd] = K_lds + KB * SHMK + kswz<DQK>(r32, (dd * 16 + hi * 8) * 2);
; #pragma unroll
;     for (int d0 = 0; d0 < NF; ++d0) { const char* a = kb[d0 & 3] + (d0 >> 2) * 128;
;         bf16x8 b0 = *reinterpret_cast<const bf16x8*>(a);
;         bf16x8 b1 = *reinterpret_cast<const bf16x8*>(a + 32 * DQK * 2);
;         bf16x8 q; if (d0 < NFR) q = qr[d0]; else q = *reinterpret_cast<const bf16x8*>(qrl + (d0 - NFR) * 1024);
;         p0 = __builtin_amdgcn_mfma_f32_32x32x16_bf16(b0, q, p0, 0, 0, 0);
;         p1 = __builtin_amdgcn_mfma_f32_32x32x16_bf16(b1, q, p1, 0, 0, 0); }
.LBB0_693:
	ds_read_b128 v[66:69], v161 offset:40960
	ds_read_b128 v[70:73], v161 offset:45056
	v_add_f32_e32 v0, 0, v149
	v_add_f32_e32 v0, v186, v0
	v_add_f32_e32 v0, v147, v0
	s_waitcnt lgkmcnt(1)
	v_mfma_f32_32x32x16_bf16 v[82:97], v[66:69], v[110:113], 0
	v_add_f32_e32 v0, v183, v0
	v_add_f32_e32 v0, v141, v0
	ds_read_b128 v[188:191], v162 offset:40960
	ds_read_b128 v[192:195], v162 offset:45056
	v_add_f32_e32 v0, v148, v0
	v_add_f32_e32 v0, v140, v0
	v_add_f32_e32 v0, v146, v0
	v_add_f32_e32 v0, v137, v0
	s_waitcnt lgkmcnt(2)
	v_mfma_f32_32x32x16_bf16 v[66:81], v[70:73], v[110:113], 0
	v_add_f32_e32 v0, v139, v0
	v_add_f32_e32 v0, v135, v0
	v_add_f32_e32 v0, v138, v0
	v_exp_f32_e32 v122, v122
	v_add_f32_e32 v0, v133, v0
	v_exp_f32_e32 v123, v123
	v_add_f32_e32 v0, v136, v0
	s_waitcnt lgkmcnt(1)
	v_mfma_f32_32x32x16_bf16 v[82:97], v[188:191], v[106:109], v[82:97]
	v_exp_f32_e32 v131, v126
	v_add_f32_e32 v0, v132, v0
	v_exp_f32_e32 v167, v127
	v_add_f32_e32 v0, v134, v0
	v_exp_f32_e32 v114, v114
	v_add_f32_e32 v0, v122, v0
	v_exp_f32_e32 v115, v115
	s_waitcnt lgkmcnt(0)
	v_mfma_f32_32x32x16_bf16 v[66:81], v[192:195], v[106:109], v[66:81]
	ds_read_b128 v[188:191], v163 offset:40960
	ds_read_b128 v[192:195], v163 offset:45056
	v_add_f32_e32 v0, v123, v0
	v_exp_f32_e32 v120, v120
	v_add_f32_e32 v0, v131, v0
	v_exp_f32_e32 v121, v121
	v_add_f32_e32 v0, v167, v0
	v_exp_f32_e32 v124, v124
	s_waitcnt lgkmcnt(1)
	v_mfma_f32_32x32x16_bf16 v[82:97], v[188:191], v[102:105], v[82:97]
	v_add_f32_e32 v0, v114, v0
	v_exp_f32_e32 v125, v125
	v_add_f32_e32 v0, v115, v0
	v_exp_f32_e32 v170, v128
	v_add_f32_e32 v0, v120, v0
	v_exp_f32_e32 v171, v129
	v_add_f32_e32 v0, v121, v0
	s_waitcnt lgkmcnt(0)
	v_mfma_f32_32x32x16_bf16 v[66:81], v[192:195], v[102:105], v[66:81]
	ds_read_b128 v[188:191], v164 offset:40960
	ds_read_b128 v[192:195], v164 offset:45056
	v_exp_f32_e32 v116, v116
	v_add_f32_e32 v0, v124, v0
	v_exp_f32_e32 v117, v117
	v_add_f32_e32 v0, v125, v0
	v_exp_f32_e32 v118, v118
	v_add_f32_e32 v0, v170, v0
	s_waitcnt lgkmcnt(1)
	v_mfma_f32_32x32x16_bf16 v[82:97], v[188:191], v[98:101], v[82:97]
	v_exp_f32_e32 v119, v119
	v_add_f32_e32 v0, v171, v0
	v_add_f32_e32 v0, v116, v0
	v_add_f32_e32 v0, v117, v0
	v_add_f32_e32 v0, v118, v0
	v_add_f32_e32 v0, v119, v0
	v_mov_b32_e32 v181, v0
	s_waitcnt lgkmcnt(0)
	v_mfma_f32_32x32x16_bf16 v[66:81], v[192:195], v[98:101], v[66:81]
	v_cvt_pk_bf16_f32 v126, v149, v186
	v_cvt_pk_bf16_f32 v127, v147, v183
	v_cvt_pk_bf16_f32 v128, v141, v148
	v_permlane32_swap_b32_e32 v0, v181
	v_cvt_pk_bf16_f32 v129, v140, v146
	v_permlane32_swap_b32_e32 v126, v128
	v_cvt_pk_bf16_f32 v182, v137, v139
	v_cvt_pk_bf16_f32 v183, v135, v138
	v_cvt_pk_bf16_f32 v184, v133, v136
	v_cvt_pk_bf16_f32 v185, v132, v134
	v_cvt_pk_bf16_f32 v132, v122, v123
	v_cvt_pk_bf16_f32 v133, v131, v167
	v_cvt_pk_bf16_f32 v134, v114, v115
	v_cvt_pk_bf16_f32 v135, v120, v121
	v_cvt_pk_bf16_f32 v136, v124, v125
	v_cvt_pk_bf16_f32 v137, v170, v171
	v_cvt_pk_bf16_f32 v138, v116, v117
	v_cvt_pk_bf16_f32 v139, v118, v119
	v_permlane32_swap_b32_e32 v127, v129
	v_permlane32_swap_b32_e32 v182, v184
	v_permlane32_swap_b32_e32 v183, v185
	v_permlane32_swap_b32_e32 v132, v134
	v_permlane32_swap_b32_e32 v133, v135
	v_permlane32_swap_b32_e32 v136, v138
	v_permlane32_swap_b32_e32 v137, v139
	v_lshl_add_u64 v[146:147], v[142:143], 0, s[26:27]
	v_add_co_u32_e32 v114, vcc, s20, v146
	s_mov_b32 s4, 0x18cb4000
	s_nop 0
	v_addc_co_u32_e32 v115, vcc, 0, v147, vcc
	v_add_co_u32_e32 v118, vcc, s4, v146
	v_lshl_add_u64 v[148:149], v[144:145], 0, s[26:27]
	s_nop 0
	v_addc_co_u32_e32 v119, vcc, 0, v147, vcc
	v_add_co_u32_e32 v122, vcc, s20, v148
	global_load_dwordx4 v[114:117], v[114:115], off offset:3456
	s_nop 0
	global_load_dwordx4 v[118:121], v[118:119], off offset:3456
	v_addc_co_u32_e32 v123, vcc, 0, v149, vcc
	global_load_dwordx4 v[122:125], v[122:123], off offset:2432
	ds_read_b64_tr_b16 v[186:187], v153 offset:0
	ds_read_b64_tr_b16 v[188:189], v153 offset:0x800
	ds_read_b64_tr_b16 v[190:191], v153 offset:0x1000
	ds_read_b64_tr_b16 v[192:193], v153 offset:0x1800
	ds_read_b64_tr_b16 v[194:195], v153 offset:0x2000
	ds_read_b64_tr_b16 v[196:197], v153 offset:0x2800
	ds_read_b64_tr_b16 v[208:209], v153 offset:0x3000
	ds_read_b64_tr_b16 v[210:211], v153 offset:0x3800
	s_waitcnt lgkmcnt(15)
	s_nop 0
	s_waitcnt lgkmcnt(6)
	v_mfma_f32_32x32x16_bf16 v[50:65], v[126:129], v[186:189], v[50:65]
	ds_read_b64_tr_b16 v[186:187], v153 offset:0x200
	ds_read_b64_tr_b16 v[188:189], v153 offset:0xa00
	s_waitcnt lgkmcnt(6)
	v_mfma_f32_32x32x16_bf16 v[50:65], v[182:185], v[190:193], v[50:65]
	ds_read_b64_tr_b16 v[190:191], v153 offset:0x1200
	ds_read_b64_tr_b16 v[192:193], v153 offset:0x1a00
	s_waitcnt lgkmcnt(6)
	v_mfma_f32_32x32x16_bf16 v[50:65], v[132:135], v[194:197], v[50:65]
	ds_read_b64_tr_b16 v[194:195], v153 offset:0x2200
	ds_read_b64_tr_b16 v[196:197], v153 offset:0x2a00
	s_waitcnt lgkmcnt(6)
	v_mfma_f32_32x32x16_bf16 v[50:65], v[136:139], v[208:211], v[50:65]
	ds_read_b64_tr_b16 v[208:209], v153 offset:0x3200
	ds_read_b64_tr_b16 v[210:211], v153 offset:0x3a00
	s_waitcnt lgkmcnt(15)
	s_waitcnt lgkmcnt(6)
	v_mfma_f32_32x32x16_bf16 v[34:49], v[126:129], v[186:189], v[34:49]
	ds_read_b64_tr_b16 v[186:187], v153 offset:0x400
	ds_read_b64_tr_b16 v[188:189], v153 offset:0xc00
	s_waitcnt lgkmcnt(6)
	v_mfma_f32_32x32x16_bf16 v[34:49], v[182:185], v[190:193], v[34:49]
	ds_read_b64_tr_b16 v[190:191], v153 offset:0x1400
	ds_read_b64_tr_b16 v[192:193], v153 offset:0x1c00
	s_waitcnt lgkmcnt(6)
	v_mfma_f32_32x32x16_bf16 v[34:49], v[132:135], v[194:197], v[34:49]
	ds_read_b64_tr_b16 v[194:195], v153 offset:0x2400
	ds_read_b64_tr_b16 v[196:197], v153 offset:0x2c00
	s_waitcnt lgkmcnt(6)
; __device__ __forceinline__ void bias_tile(f32x16& p0, f32x16& p1, int dq, const float* tb) {
; #pragma unroll
;     for (int r = 0; r < 16; ++r) {
;         const int c = (r & 3) + 8 * (r >> 2);
;         int d0 = dq - c, d1 = dq - c - 32;
;         d0 = d0 < 0 ? 0 : (d0 > 127 ? 127 : d0); d1 = d1 < 0 ? 0 : (d1 > 127 ? 127 : d1);
;         p0[r] += tb[d0]; p1[r] += tb[d1];
;     }
; }
; template <int VB>
; __device__ __forceinline__ void pv_tile(f32x16* o, int vb0, bf16x8 pa0, bf16x8 pa1, bf16x8 pa2, bf16x8 pa3) {
;     ...
;     PV_D0(0); PV_D0(1); PV_D0(2); PV_D0(3);
	v_mfma_f32_32x32x16_bf16 v[34:49], v[136:139], v[208:211], v[34:49]
	ds_read_b64_tr_b16 v[208:209], v153 offset:0x3400
	ds_read_b64_tr_b16 v[210:211], v153 offset:0x3c00
	s_waitcnt lgkmcnt(15)
	s_waitcnt lgkmcnt(6)
	v_mfma_f32_32x32x16_bf16 v[18:33], v[126:129], v[186:189], v[18:33]
	ds_read_b64_tr_b16 v[186:187], v153 offset:0x600
	ds_read_b64_tr_b16 v[188:189], v153 offset:0xe00
	s_waitcnt lgkmcnt(6)
	v_mfma_f32_32x32x16_bf16 v[18:33], v[182:185], v[190:193], v[18:33]
	ds_read_b64_tr_b16 v[190:191], v153 offset:0x1600
	ds_read_b64_tr_b16 v[192:193], v153 offset:0x1e00
	s_waitcnt lgkmcnt(6)
	v_mfma_f32_32x32x16_bf16 v[18:33], v[132:135], v[194:197], v[18:33]
	ds_read_b64_tr_b16 v[194:195], v153 offset:0x2600
	ds_read_b64_tr_b16 v[196:197], v153 offset:0x2e00
	s_waitcnt lgkmcnt(6)
	v_mfma_f32_32x32x16_bf16 v[18:33], v[136:139], v[208:211], v[18:33]
	ds_read_b64_tr_b16 v[208:209], v153 offset:0x3600
	ds_read_b64_tr_b16 v[210:211], v153 offset:0x3e00
	s_waitcnt lgkmcnt(15)
	s_waitcnt lgkmcnt(6)
	v_mfma_f32_32x32x16_bf16 v[2:17], v[126:129], v[186:189], v[2:17]
	s_add_i32 s4, s21, 49
	s_cmp_le_i32 s4, s30
	v_add_u32_e32 v126, 0x5b, v180
	s_waitcnt lgkmcnt(4)
	v_mfma_f32_32x32x16_bf16 v[2:17], v[182:185], v[190:193], v[2:17]
	s_waitcnt lgkmcnt(2)
	v_mfma_f32_32x32x16_bf16 v[2:17], v[132:135], v[194:197], v[2:17]
	s_waitcnt lgkmcnt(0)
	v_mfma_f32_32x32x16_bf16 v[2:17], v[136:139], v[208:211], v[2:17]
	s_cbranch_scc1 .LBB0_695
	v_med3_i32 v128, v126, 32, v206
	v_lshl_add_u32 v128, v128, 2, s33
	v_add_u32_e32 v129, 0xffffff80, v128
	v_add_u32_e32 v128, 0x5a, v180
	v_med3_i32 v131, v128, 0, v205
	v_med3_i32 v128, v128, 32, v206
	v_lshl_add_u32 v128, v128, 2, s33
	v_add_u32_e32 v133, 0xffffff80, v128
	v_add_u32_e32 v128, 0x59, v180
	v_med3_i32 v132, v128, 0, v205
	v_med3_i32 v128, v128, 32, v206
	v_lshl_add_u32 v128, v128, 2, s33
	v_add_u32_e32 v135, 0xffffff80, v128
	v_add_u32_e32 v128, 0x58, v180
	v_lshl_add_u32 v134, v132, 2, s33
	v_med3_i32 v132, v128, 0, v205
	v_med3_i32 v128, v128, 32, v206
	v_med3_i32 v127, v126, 0, v205
	v_lshl_add_u32 v128, v128, 2, s33
	v_lshl_add_u32 v127, v127, 2, s33
	v_lshl_add_u32 v137, v132, 2, s33
	v_add_u32_e32 v138, 0xffffff80, v128
	v_lshl_add_u32 v131, v131, 2, s33
	ds_read_b32 v128, v127
	ds_read_b32 v132, v129
	ds_read_b32 v129, v131
	ds_read_b32 v133, v133
	ds_read_b32 v134, v134
	ds_read_b32 v136, v135
	ds_read_b32 v135, v137
	ds_read_b32 v137, v138
	v_add_u32_e32 v138, 0x52, v180
	v_med3_i32 v139, v138, 0, v205
	v_med3_i32 v138, v138, 32, v206
	v_lshl_add_u32 v138, v138, 2, s33
	v_add_u32_e32 v141, 0xffffff80, v138
	v_add_u32_e32 v138, 0x51, v180
	v_med3_i32 v140, v138, 0, v205
	v_med3_i32 v138, v138, 32, v206
	v_add_u32_e32 v127, 0x53, v180
	v_lshl_add_u32 v138, v138, 2, s33
	v_med3_i32 v131, v127, 0, v205
	v_med3_i32 v127, v127, 32, v206
	v_add_u32_e32 v170, 0xffffff80, v138
	v_add_u32_e32 v138, 0x50, v180
	v_lshl_add_u32 v127, v127, 2, s33
	v_lshl_add_u32 v167, v140, 2, s33
	v_med3_i32 v140, v138, 0, v205
	v_med3_i32 v138, v138, 32, v206
	v_lshl_add_u32 v131, v131, 2, s33
	v_add_u32_e32 v127, 0xffffff80, v127
	v_lshl_add_u32 v139, v139, 2, s33
	v_lshl_add_u32 v171, v140, 2, s33
	v_lshl_add_u32 v138, v138, 2, s33
	v_add_u32_e32 v176, 0xffffff80, v138
	ds_read_b32 v138, v131
	ds_read_b32 v140, v127
	ds_read_b32 v139, v139
	ds_read_b32 v141, v141
	ds_read_b32 v182, v167
	ds_read_b32 v184, v170
	ds_read_b32 v183, v171
	ds_read_b32 v185, v176
	v_add_u32_e32 v127, 0x4b, v180
	v_add_u32_e32 v167, 0x4a, v180
	v_add_u32_e32 v171, 0x49, v180
	v_add_u32_e32 v177, 0x48, v180
	v_med3_i32 v131, v127, 0, v205
	v_med3_i32 v127, v127, 32, v206
	v_med3_i32 v170, v167, 0, v205
	v_med3_i32 v167, v167, 32, v206
	v_med3_i32 v176, v171, 0, v205
	v_med3_i32 v171, v171, 32, v206
	v_med3_i32 v186, v177, 0, v205
	v_med3_i32 v177, v177, 32, v206
	v_lshl_add_u32 v127, v127, 2, s33
	v_lshl_add_u32 v167, v167, 2, s33
	v_lshl_add_u32 v171, v171, 2, s33
	v_lshl_add_u32 v177, v177, 2, s33
	v_lshl_add_u32 v131, v131, 2, s33
	v_add_u32_e32 v127, 0xffffff80, v127
	v_add_u32_e32 v167, 0xffffff80, v167
	v_add_u32_e32 v171, 0xffffff80, v171
	v_lshl_add_u32 v191, v186, 2, s33
	v_add_u32_e32 v177, 0xffffff80, v177
	v_lshl_add_u32 v170, v170, 2, s33
	v_lshl_add_u32 v176, v176, 2, s33
	ds_read_b32 v186, v131
	ds_read_b32 v188, v127
	ds_read_b32 v187, v170
	ds_read_b32 v189, v167
	ds_read_b32 v190, v176
	ds_read_b32 v192, v171
	ds_read_b32 v191, v191
	ds_read_b32 v193, v177
	v_add_u32_e32 v127, 0x43, v180
	v_add_u32_e32 v167, 0x42, v180
	v_add_u32_e32 v171, 0x41, v180
	v_add_u32_e32 v177, 64, v180
	v_med3_i32 v131, v127, 0, v205
	v_med3_i32 v127, v127, 32, v206
	v_med3_i32 v170, v167, 0, v205
	v_med3_i32 v167, v167, 32, v206
	v_med3_i32 v176, v171, 0, v205
	v_med3_i32 v171, v171, 32, v206
	v_med3_i32 v194, v177, 0, v205
	v_med3_i32 v177, v177, 32, v206
	v_lshl_add_u32 v131, v131, 2, s33
	v_lshl_add_u32 v127, v127, 2, s33
	v_lshl_add_u32 v167, v167, 2, s33
	v_lshl_add_u32 v171, v171, 2, s33
	v_lshl_add_u32 v195, v194, 2, s33
	v_lshl_add_u32 v177, v177, 2, s33
	v_add_u32_e32 v127, 0xffffff80, v127
	v_lshl_add_u32 v170, v170, 2, s33
	v_add_u32_e32 v167, 0xffffff80, v167
	v_lshl_add_u32 v176, v176, 2, s33
	v_add_u32_e32 v171, 0xffffff80, v171
	v_add_u32_e32 v177, 0xffffff80, v177
	ds_read_b32 v194, v131
	ds_read_b32 v196, v127
	ds_read_b32 v208, v176
	ds_read_b32 v209, v195
	ds_read_b32 v195, v170
	ds_read_b32 v211, v177
	ds_read_b32 v210, v171
	ds_read_b32 v197, v167
	s_waitcnt lgkmcnt(4)
	v_pk_add_f32 v[96:97], v[96:97], v[208:209]
	s_waitcnt lgkmcnt(3)
	v_pk_add_f32 v[94:95], v[94:95], v[194:195]
	v_pk_add_f32 v[92:93], v[92:93], v[190:191]
	v_pk_add_f32 v[90:91], v[90:91], v[186:187]
	v_pk_add_f32 v[88:89], v[88:89], v[182:183]
	v_pk_add_f32 v[86:87], v[86:87], v[138:139]
	v_pk_add_f32 v[84:85], v[84:85], v[134:135]
	v_pk_add_f32 v[82:83], v[82:83], v[128:129]
	s_waitcnt lgkmcnt(1)
	v_pk_add_f32 v[80:81], v[80:81], v[210:211]
	s_waitcnt lgkmcnt(0)
	v_pk_add_f32 v[78:79], v[78:79], v[196:197]
	v_pk_add_f32 v[76:77], v[76:77], v[192:193]
	v_pk_add_f32 v[74:75], v[74:75], v[188:189]
	v_pk_add_f32 v[72:73], v[72:73], v[184:185]
	v_pk_add_f32 v[70:71], v[70:71], v[140:141]
	v_pk_add_f32 v[68:69], v[68:69], v[136:137]
	v_pk_add_f32 v[66:67], v[66:67], v[132:133]

; template <int VB>
; __device__ __forceinline__ void pv_tile(f32x16* o, int vb0, bf16x8 pa0, bf16x8 pa1, bf16x8 pa2, bf16x8 pa3) {
;     ...
;     PV_D0(0); PV_D0(1); PV_D0(2); PV_D0(3);
.LBB0_703:
	ds_read_b64_tr_b16 v[146:147], v153 offset:0x4000
	ds_read_b64_tr_b16 v[148:149], v153 offset:0x4800
	ds_read_b64_tr_b16 v[186:187], v153 offset:0x5000
	ds_read_b64_tr_b16 v[188:189], v153 offset:0x5800
	ds_read_b64_tr_b16 v[190:191], v153 offset:0x6000
	ds_read_b64_tr_b16 v[192:193], v153 offset:0x6800
	ds_read_b64_tr_b16 v[194:195], v153 offset:0x7000
	ds_read_b64_tr_b16 v[196:197], v153 offset:0x7800
	s_waitcnt lgkmcnt(15)
	s_nop 0
	s_waitcnt lgkmcnt(6)
	v_mfma_f32_32x32x16_bf16 v[50:65], v[126:129], v[146:149], v[50:65]
	ds_read_b64_tr_b16 v[146:147], v153 offset:0x4200
	ds_read_b64_tr_b16 v[148:149], v153 offset:0x4a00
	s_waitcnt lgkmcnt(6)
	v_mfma_f32_32x32x16_bf16 v[50:65], v[130:133], v[186:189], v[50:65]
	ds_read_b64_tr_b16 v[186:187], v153 offset:0x5200
	ds_read_b64_tr_b16 v[188:189], v153 offset:0x5a00
	s_waitcnt lgkmcnt(6)
	v_mfma_f32_32x32x16_bf16 v[50:65], v[138:141], v[190:193], v[50:65]
	ds_read_b64_tr_b16 v[190:191], v153 offset:0x6200
	ds_read_b64_tr_b16 v[192:193], v153 offset:0x6a00
	s_waitcnt lgkmcnt(6)
	v_mfma_f32_32x32x16_bf16 v[50:65], v[134:137], v[194:197], v[50:65]
	ds_read_b64_tr_b16 v[194:195], v153 offset:0x7200
	ds_read_b64_tr_b16 v[196:197], v153 offset:0x7a00
	s_waitcnt lgkmcnt(15)
	s_waitcnt lgkmcnt(6)
	v_mfma_f32_32x32x16_bf16 v[34:49], v[126:129], v[146:149], v[34:49]
	ds_read_b64_tr_b16 v[146:147], v153 offset:0x4400
	ds_read_b64_tr_b16 v[148:149], v153 offset:0x4c00
	s_waitcnt lgkmcnt(6)
	v_mfma_f32_32x32x16_bf16 v[34:49], v[130:133], v[186:189], v[34:49]
	ds_read_b64_tr_b16 v[186:187], v153 offset:0x5400
	ds_read_b64_tr_b16 v[188:189], v153 offset:0x5c00
	s_waitcnt lgkmcnt(6)
	v_mfma_f32_32x32x16_bf16 v[34:49], v[138:141], v[190:193], v[34:49]
	ds_read_b64_tr_b16 v[190:191], v153 offset:0x6400
	ds_read_b64_tr_b16 v[192:193], v153 offset:0x6c00
	s_waitcnt lgkmcnt(6)
	v_mfma_f32_32x32x16_bf16 v[34:49], v[134:137], v[194:197], v[34:49]
	ds_read_b64_tr_b16 v[194:195], v153 offset:0x7400
	ds_read_b64_tr_b16 v[196:197], v153 offset:0x7c00
	s_waitcnt lgkmcnt(15)
	s_waitcnt lgkmcnt(6)
	v_mfma_f32_32x32x16_bf16 v[18:33], v[126:129], v[146:149], v[18:33]
	ds_read_b64_tr_b16 v[146:147], v153 offset:0x4600
	ds_read_b64_tr_b16 v[148:149], v153 offset:0x4e00
	s_waitcnt lgkmcnt(6)
	v_mfma_f32_32x32x16_bf16 v[18:33], v[130:133], v[186:189], v[18:33]
	ds_read_b64_tr_b16 v[186:187], v153 offset:0x5600
	ds_read_b64_tr_b16 v[188:189], v153 offset:0x5e00
	s_waitcnt lgkmcnt(6)
	v_mfma_f32_32x32x16_bf16 v[18:33], v[138:141], v[190:193], v[18:33]
	ds_read_b64_tr_b16 v[190:191], v153 offset:0x6600
	ds_read_b64_tr_b16 v[192:193], v153 offset:0x6e00
	s_waitcnt lgkmcnt(6)
	v_mfma_f32_32x32x16_bf16 v[18:33], v[134:137], v[194:197], v[18:33]
	ds_read_b64_tr_b16 v[194:195], v153 offset:0x7600
	ds_read_b64_tr_b16 v[196:197], v153 offset:0x7e00
	s_waitcnt lgkmcnt(15)
	s_waitcnt lgkmcnt(6)
	v_mfma_f32_32x32x16_bf16 v[2:17], v[126:129], v[146:149], v[2:17]
	s_add_i32 s4, s21, 0x71
	s_cmp_le_i32 s4, s30
	v_add_u32_e32 v126, 27, v180
	s_waitcnt lgkmcnt(4)
	v_mfma_f32_32x32x16_bf16 v[2:17], v[130:133], v[186:189], v[2:17]
	s_waitcnt lgkmcnt(2)
	v_mfma_f32_32x32x16_bf16 v[2:17], v[138:141], v[190:193], v[2:17]
	s_waitcnt lgkmcnt(0)
	v_mfma_f32_32x32x16_bf16 v[2:17], v[134:137], v[194:197], v[2:17]
	s_cbranch_scc1 .LBB0_705
; __device__ __forceinline__ void bias_tile(f32x16& p0, f32x16& p1, int dq, const float* tb) {
; #pragma unroll
;     for (int r = 0; r < 16; ++r) {
;         const int c = (r & 3) + 8 * (r >> 2);
;         int d0 = dq - c, d1 = dq - c - 32;
;         d0 = d0 < 0 ? 0 : (d0 > 127 ? 127 : d0); d1 = d1 < 0 ? 0 : (d1 > 127 ? 127 : d1);
;         p0[r] += tb[d0]; p1[r] += tb[d1];
;     }
; }
	v_med3_i32 v128, v126, 32, v206
	v_lshl_add_u32 v128, v128, 2, s33
	v_add_u32_e32 v129, 0xffffff80, v128
	v_add_u32_e32 v128, 26, v180
	v_med3_i32 v130, v128, 0, v205
	v_med3_i32 v128, v128, 32, v206
	v_lshl_add_u32 v128, v128, 2, s33
	v_add_u32_e32 v132, 0xffffff80, v128
	v_add_u32_e32 v128, 25, v180
	v_lshl_add_u32 v131, v130, 2, s33
	v_med3_i32 v130, v128, 0, v205
	v_med3_i32 v128, v128, 32, v206
	v_add_u32_e32 v137, 18, v180
	v_lshl_add_u32 v128, v128, 2, s33
	v_med3_i32 v138, v137, 0, v205
	v_med3_i32 v137, v137, 32, v206
	v_add_u32_e32 v134, 0xffffff80, v128
	v_add_u32_e32 v128, 24, v180
	v_lshl_add_u32 v137, v137, 2, s33
	v_med3_i32 v127, v126, 0, v205
	v_lshl_add_u32 v133, v130, 2, s33
	v_med3_i32 v130, v128, 0, v205
	v_med3_i32 v128, v128, 32, v206
	v_add_u32_e32 v140, 0xffffff80, v137
	v_add_u32_e32 v137, 17, v180
	v_add_u32_e32 v149, 10, v180
	v_lshl_add_u32 v127, v127, 2, s33
	v_lshl_add_u32 v135, v130, 2, s33
	v_lshl_add_u32 v128, v128, 2, s33
	v_lshl_add_u32 v139, v138, 2, s33
	v_med3_i32 v138, v137, 0, v205
	v_med3_i32 v137, v137, 32, v206
	v_med3_i32 v167, v149, 0, v205
	v_med3_i32 v149, v149, 32, v206
	v_add_u32_e32 v136, 0xffffff80, v128
	ds_read_b32 v128, v127
	ds_read_b32 v130, v129
	ds_read_b32 v129, v131
	ds_read_b32 v131, v132
	ds_read_b32 v132, v133
	ds_read_b32 v134, v134
	ds_read_b32 v133, v135
	ds_read_b32 v135, v136
	v_add_u32_e32 v127, 19, v180
	v_lshl_add_u32 v137, v137, 2, s33
	v_lshl_add_u32 v149, v149, 2, s33
	v_med3_i32 v136, v127, 0, v205
	v_med3_i32 v127, v127, 32, v206
	v_add_u32_e32 v146, 0xffffff80, v137
	v_add_u32_e32 v137, 16, v180
	v_add_u32_e32 v170, 0xffffff80, v149
	v_add_u32_e32 v149, 9, v180
	v_lshl_add_u32 v127, v127, 2, s33
	v_lshl_add_u32 v141, v138, 2, s33
	v_med3_i32 v138, v137, 0, v205
	v_med3_i32 v137, v137, 32, v206
	v_med3_i32 v171, v149, 0, v205
	v_med3_i32 v149, v149, 32, v206
	v_lshl_add_u32 v136, v136, 2, s33
	v_add_u32_e32 v127, 0xffffff80, v127
	v_lshl_add_u32 v147, v138, 2, s33
	v_lshl_add_u32 v137, v137, 2, s33
	v_lshl_add_u32 v149, v149, 2, s33
	v_add_u32_e32 v148, 0xffffff80, v137
	ds_read_b32 v136, v136
	ds_read_b32 v138, v127
	ds_read_b32 v137, v139
	ds_read_b32 v139, v140
	ds_read_b32 v140, v141
	ds_read_b32 v146, v146
	ds_read_b32 v141, v147
	ds_read_b32 v147, v148
	v_add_u32_e32 v127, 11, v180
	v_add_u32_e32 v176, 0xffffff80, v149
	v_add_u32_e32 v149, 8, v180
	v_med3_i32 v148, v127, 0, v205
	v_med3_i32 v127, v127, 32, v206
	v_med3_i32 v177, v149, 0, v205
	v_med3_i32 v149, v149, 32, v206
	v_lshl_add_u32 v127, v127, 2, s33
	v_lshl_add_u32 v149, v149, 2, s33
	v_lshl_add_u32 v148, v148, 2, s33
	v_add_u32_e32 v127, 0xffffff80, v127
	v_add_u32_e32 v191, 0xffffff80, v149
	v_lshl_add_u32 v167, v167, 2, s33
	v_lshl_add_u32 v171, v171, 2, s33
	v_lshl_add_u32 v177, v177, 2, s33
	ds_read_b32 v148, v148
	ds_read_b32 v186, v127
	ds_read_b32 v149, v167
	ds_read_b32 v187, v170
	ds_read_b32 v188, v171
	ds_read_b32 v190, v176
	ds_read_b32 v189, v177
	ds_read_b32 v191, v191
	v_add_u32_e32 v127, 3, v180
	v_add_u32_e32 v170, 2, v180
	v_add_u32_e32 v176, 1, v180
	v_med3_i32 v167, v127, 0, v205
	v_med3_i32 v127, v127, 32, v206
	v_med3_i32 v171, v170, 0, v205
	v_med3_i32 v170, v170, 32, v206
	v_med3_i32 v177, v176, 0, v205
	v_med3_i32 v176, v176, 32, v206
	v_med3_i32 v192, v180, 0, v205
	v_med3_i32 v193, v180, 32, v206
	v_lshl_add_u32 v167, v167, 2, s33
	v_lshl_add_u32 v127, v127, 2, s33
	v_lshl_add_u32 v170, v170, 2, s33
	v_lshl_add_u32 v176, v176, 2, s33
	v_lshl_add_u32 v195, v192, 2, s33
	v_lshl_add_u32 v192, v193, 2, s33
	v_add_u32_e32 v127, 0xffffff80, v127
	v_lshl_add_u32 v171, v171, 2, s33
	v_add_u32_e32 v170, 0xffffff80, v170
	v_lshl_add_u32 v177, v177, 2, s33
	v_add_u32_e32 v176, 0xffffff80, v176
	v_add_u32_e32 v202, 0xffffff80, v192
	ds_read_b32 v192, v167
	ds_read_b32 v194, v127
	ds_read_b32 v196, v177
	ds_read_b32 v197, v195
	ds_read_b32 v193, v171
	ds_read_b32 v209, v202
	ds_read_b32 v208, v176
	ds_read_b32 v195, v170
	s_waitcnt lgkmcnt(4)
	v_pk_add_f32 v[96:97], v[96:97], v[196:197]
	s_waitcnt lgkmcnt(3)
	v_pk_add_f32 v[94:95], v[94:95], v[192:193]
	v_pk_add_f32 v[92:93], v[92:93], v[188:189]
	v_pk_add_f32 v[90:91], v[90:91], v[148:149]
	v_pk_add_f32 v[88:89], v[88:89], v[140:141]
	v_pk_add_f32 v[86:87], v[86:87], v[136:137]
	v_pk_add_f32 v[84:85], v[84:85], v[132:133]
	v_pk_add_f32 v[82:83], v[82:83], v[128:129]
	s_waitcnt lgkmcnt(1)
	v_pk_add_f32 v[80:81], v[80:81], v[208:209]
	s_waitcnt lgkmcnt(0)
	v_pk_add_f32 v[78:79], v[78:79], v[194:195]
	v_pk_add_f32 v[76:77], v[76:77], v[190:191]
	v_pk_add_f32 v[74:75], v[74:75], v[186:187]
	v_pk_add_f32 v[72:73], v[72:73], v[146:147]
	v_pk_add_f32 v[70:71], v[70:71], v[138:139]
	v_pk_add_f32 v[68:69], v[68:69], v[134:135]
	v_pk_add_f32 v[66:67], v[66:67], v[130:131]

; __device__ __forceinline__ void finishSM(f32x16& p0, f32x16& p1, float alpha, float& l_reg, bf16x8& pa0, bf16x8& pa1, bf16x8& pa2, bf16x8& pa3) {
; #pragma unroll
;     for (int r = 0; r < 16; ++r) p1[r] = __builtin_amdgcn_exp2f(p1[r]);
;     float ps = 0;
; #pragma unroll
;     for (int r = 0; r < 16; ++r) ps += p0[r];
; #pragma unroll
;     for (int r = 0; r < 16; ++r) ps += p1[r];
;     { auto rr = __builtin_amdgcn_permlane32_swap(__float_as_uint(ps), __float_as_uint(ps), false, false);
;       ps = __uint_as_float(rr[0]) + __uint_as_float(rr[1]); }
;     l_reg = l_reg * alpha + ps;
;     ...
;     PK4(p0, 0, pa0); PK4(p0, 8, pa1); PK4(p1, 0, pa2); PK4(p1, 8, pa3);
;     ...
; }
; template <int KB, int DQK>
; __device__ __forceinline__ void qkt(f32x16& p0, f32x16& p1, const char* K_lds, int r32, int hi, const bf16x8* qr, const char* qrl) {
;     constexpr int SHMK = 64 * DQK * 2, NF = DQK / 16, NFR = NF > 8 ? 8 : NF;
;     p0 = f32x16{}; p1 = f32x16{};
;     const char* kb[4];
; #pragma unroll
;     for (int dd = 0; dd < 4; ++dd) kb[dd] = K_lds + KB * SHMK + kswz<DQK>(r32, (dd * 16 + hi * 8) * 2);
; #pragma unroll
;     for (int d0 = 0; d0 < NF; ++d0) { const char* a = kb[d0 & 3] + (d0 >> 2) * 128;
;         bf16x8 b0 = *reinterpret_cast<const bf16x8*>(a);
;         bf16x8 b1 = *reinterpret_cast<const bf16x8*>(a + 32 * DQK * 2);
;         bf16x8 q; if (d0 < NFR) q = qr[d0]; else q = *reinterpret_cast<const bf16x8*>(qrl + (d0 - NFR) * 1024);
;         p0 = __builtin_amdgcn_mfma_f32_32x32x16_bf16(b0, q, p0, 0, 0, 0);
;         p1 = __builtin_amdgcn_mfma_f32_32x32x16_bf16(b1, q, p1, 0, 0, 0); }
; }
; template <int VB>
; __device__ __forceinline__ void pv_tile(f32x16* o, int vb0, bf16x8 pa0, bf16x8 pa1, bf16x8 pa2, bf16x8 pa3) {
;     ...
;     PV_D0(0); PV_D0(1); PV_D0(2); PV_D0(3);
;     ...
; }
.LBB0_715:
	ds_read_b128 v[66:69], v161 offset:40960
	ds_read_b128 v[70:73], v161 offset:45056
	s_waitcnt lgkmcnt(1)
	v_mfma_f32_32x32x16_bf16 v[82:97], v[66:69], v[110:113], 0
	s_waitcnt lgkmcnt(0)
	v_mfma_f32_32x32x16_bf16 v[66:81], v[70:73], v[110:113], 0
	ds_read_b128 v[110:113], v162 offset:40960
	ds_read_b128 v[142:145], v162 offset:45056
	s_waitcnt lgkmcnt(1)
	v_mfma_f32_32x32x16_bf16 v[82:97], v[110:113], v[106:109], v[82:97]
	s_waitcnt lgkmcnt(0)
	v_mfma_f32_32x32x16_bf16 v[66:81], v[142:145], v[106:109], v[66:81]
	ds_read_b128 v[106:109], v163 offset:40960
	ds_read_b128 v[110:113], v163 offset:45056
	s_waitcnt lgkmcnt(1)
	v_mfma_f32_32x32x16_bf16 v[82:97], v[106:109], v[102:105], v[82:97]
	s_waitcnt lgkmcnt(0)
	v_mfma_f32_32x32x16_bf16 v[66:81], v[110:113], v[102:105], v[66:81]
	ds_read_b128 v[102:105], v164 offset:40960
	ds_read_b128 v[106:109], v164 offset:45056
	s_waitcnt lgkmcnt(1)
	v_mfma_f32_32x32x16_bf16 v[82:97], v[102:105], v[98:101], v[82:97]
	s_waitcnt lgkmcnt(0)
	v_mfma_f32_32x32x16_bf16 v[66:81], v[106:109], v[98:101], v[66:81]
	v_add_f32_e32 v0, 0, v149
	v_add_f32_e32 v0, v186, v0
	v_add_f32_e32 v0, v147, v0
	v_add_f32_e32 v0, v183, v0
	v_add_f32_e32 v0, v141, v0
	v_add_f32_e32 v0, v148, v0
	v_add_f32_e32 v0, v140, v0
	v_add_f32_e32 v0, v146, v0
	v_add_f32_e32 v0, v137, v0
	v_add_f32_e32 v0, v139, v0
	v_add_f32_e32 v0, v135, v0
	v_add_f32_e32 v0, v138, v0
	v_exp_f32_e32 v99, v122
	v_add_f32_e32 v0, v133, v0
	v_exp_f32_e32 v108, v123
	v_add_f32_e32 v0, v136, v0
	v_exp_f32_e32 v109, v126
	v_add_f32_e32 v0, v132, v0
	v_exp_f32_e32 v110, v127
	v_add_f32_e32 v0, v134, v0
	v_exp_f32_e32 v111, v114
	v_add_f32_e32 v0, v99, v0
	v_exp_f32_e32 v112, v115
	v_add_f32_e32 v0, v108, v0
	v_exp_f32_e32 v113, v120
	v_add_f32_e32 v0, v109, v0
	v_exp_f32_e32 v114, v121
	v_add_f32_e32 v0, v110, v0
	v_exp_f32_e32 v115, v124
	v_add_f32_e32 v0, v111, v0
	v_exp_f32_e32 v120, v125
	v_add_f32_e32 v0, v112, v0
	v_exp_f32_e32 v121, v128
	v_add_f32_e32 v0, v113, v0
	v_exp_f32_e32 v122, v129
	v_add_f32_e32 v0, v114, v0
	v_exp_f32_e32 v116, v116
	v_add_f32_e32 v0, v115, v0
	v_exp_f32_e32 v117, v117
	v_add_f32_e32 v0, v120, v0
	v_exp_f32_e32 v118, v118
	v_add_f32_e32 v0, v121, v0
	v_exp_f32_e32 v119, v119
	v_add_f32_e32 v0, v122, v0
	v_add_f32_e32 v0, v116, v0
	v_add_f32_e32 v0, v117, v0
	v_add_f32_e32 v0, v118, v0
	v_add_f32_e32 v0, v119, v0
	v_mov_b32_e32 v98, v0
	s_nop 1
	v_permlane32_swap_b32_e32 v0, v98
	v_cvt_pk_bf16_f32 v100, v149, v186
	v_cvt_pk_bf16_f32 v101, v147, v183
	v_cvt_pk_bf16_f32 v102, v141, v148
	v_cvt_pk_bf16_f32 v103, v140, v146
	v_cvt_pk_bf16_f32 v104, v137, v139
	v_cvt_pk_bf16_f32 v105, v135, v138
	v_cvt_pk_bf16_f32 v106, v133, v136
	v_cvt_pk_bf16_f32 v107, v132, v134
	v_cvt_pk_bf16_f32 v108, v99, v108
	v_cvt_pk_bf16_f32 v109, v109, v110
	v_cvt_pk_bf16_f32 v110, v111, v112
	v_cvt_pk_bf16_f32 v111, v113, v114
	v_cvt_pk_bf16_f32 v112, v115, v120
	v_cvt_pk_bf16_f32 v113, v121, v122
	v_cvt_pk_bf16_f32 v114, v116, v117
	v_cvt_pk_bf16_f32 v115, v118, v119
	s_nop 0
	v_permlane32_swap_b32_e32 v100, v102
	v_permlane32_swap_b32_e32 v101, v103
	v_permlane32_swap_b32_e32 v104, v106
	v_permlane32_swap_b32_e32 v105, v107
	v_permlane32_swap_b32_e32 v108, v110
	v_permlane32_swap_b32_e32 v109, v111
	v_permlane32_swap_b32_e32 v112, v114
	v_permlane32_swap_b32_e32 v113, v115
	ds_read_b64_tr_b16 v[116:117], v153 offset:0
	ds_read_b64_tr_b16 v[118:119], v153 offset:0x800
	ds_read_b64_tr_b16 v[120:121], v153 offset:0x1000
	ds_read_b64_tr_b16 v[122:123], v153 offset:0x1800
	ds_read_b64_tr_b16 v[124:125], v153 offset:0x2000
	ds_read_b64_tr_b16 v[126:127], v153 offset:0x2800
	ds_read_b64_tr_b16 v[132:133], v153 offset:0x3000
	ds_read_b64_tr_b16 v[134:135], v153 offset:0x3800
	s_waitcnt lgkmcnt(15)
	s_nop 0
	s_waitcnt lgkmcnt(6)
	v_mfma_f32_32x32x16_bf16 v[50:65], v[100:103], v[116:119], v[50:65]
	ds_read_b64_tr_b16 v[116:117], v153 offset:0x200
	ds_read_b64_tr_b16 v[118:119], v153 offset:0xa00
	s_waitcnt lgkmcnt(6)
	v_mfma_f32_32x32x16_bf16 v[50:65], v[104:107], v[120:123], v[50:65]
	ds_read_b64_tr_b16 v[120:121], v153 offset:0x1200
	ds_read_b64_tr_b16 v[122:123], v153 offset:0x1a00
	s_waitcnt lgkmcnt(6)
	v_mfma_f32_32x32x16_bf16 v[50:65], v[108:111], v[124:127], v[50:65]
	ds_read_b64_tr_b16 v[124:125], v153 offset:0x2200
	ds_read_b64_tr_b16 v[126:127], v153 offset:0x2a00
	s_waitcnt lgkmcnt(6)
	v_mfma_f32_32x32x16_bf16 v[50:65], v[112:115], v[132:135], v[50:65]
	ds_read_b64_tr_b16 v[132:133], v153 offset:0x3200
	ds_read_b64_tr_b16 v[134:135], v153 offset:0x3a00
	s_waitcnt lgkmcnt(15)
	s_waitcnt lgkmcnt(6)
	v_mfma_f32_32x32x16_bf16 v[34:49], v[100:103], v[116:119], v[34:49]
	ds_read_b64_tr_b16 v[116:117], v153 offset:0x400
	ds_read_b64_tr_b16 v[118:119], v153 offset:0xc00
	s_waitcnt lgkmcnt(6)
	v_mfma_f32_32x32x16_bf16 v[34:49], v[104:107], v[120:123], v[34:49]
	ds_read_b64_tr_b16 v[120:121], v153 offset:0x1400
	ds_read_b64_tr_b16 v[122:123], v153 offset:0x1c00
	s_waitcnt lgkmcnt(6)
	v_mfma_f32_32x32x16_bf16 v[34:49], v[108:111], v[124:127], v[34:49]
	ds_read_b64_tr_b16 v[124:125], v153 offset:0x2400
	ds_read_b64_tr_b16 v[126:127], v153 offset:0x2c00
	s_waitcnt lgkmcnt(6)
	v_mfma_f32_32x32x16_bf16 v[34:49], v[112:115], v[132:135], v[34:49]
	ds_read_b64_tr_b16 v[132:133], v153 offset:0x3400
	ds_read_b64_tr_b16 v[134:135], v153 offset:0x3c00
	s_waitcnt lgkmcnt(15)
	s_waitcnt lgkmcnt(6)
	v_mfma_f32_32x32x16_bf16 v[18:33], v[100:103], v[116:119], v[18:33]
	ds_read_b64_tr_b16 v[116:117], v153 offset:0x600
	ds_read_b64_tr_b16 v[118:119], v153 offset:0xe00
	s_waitcnt lgkmcnt(6)
	v_mfma_f32_32x32x16_bf16 v[18:33], v[104:107], v[120:123], v[18:33]
	ds_read_b64_tr_b16 v[120:121], v153 offset:0x1600
	ds_read_b64_tr_b16 v[122:123], v153 offset:0x1e00
	s_waitcnt lgkmcnt(6)
	v_mfma_f32_32x32x16_bf16 v[18:33], v[108:111], v[124:127], v[18:33]
	ds_read_b64_tr_b16 v[124:125], v153 offset:0x2600
	ds_read_b64_tr_b16 v[126:127], v153 offset:0x2e00
	s_waitcnt lgkmcnt(6)
	v_mfma_f32_32x32x16_bf16 v[18:33], v[112:115], v[132:135], v[18:33]
	ds_read_b64_tr_b16 v[132:133], v153 offset:0x3600
	ds_read_b64_tr_b16 v[134:135], v153 offset:0x3e00
	s_waitcnt lgkmcnt(15)
	s_waitcnt lgkmcnt(6)
	v_mfma_f32_32x32x16_bf16 v[2:17], v[100:103], v[116:119], v[2:17]
	s_or_b32 s4, s18, 0xc0
	s_cmpk_lt_i32 s31, 0x170
	v_subrev_u32_e32 v99, s4, v157
	s_waitcnt lgkmcnt(4)
	v_mfma_f32_32x32x16_bf16 v[2:17], v[104:107], v[120:123], v[2:17]
	s_waitcnt lgkmcnt(2)
	v_mfma_f32_32x32x16_bf16 v[2:17], v[108:111], v[124:127], v[2:17]
	s_waitcnt lgkmcnt(0)
	v_mfma_f32_32x32x16_bf16 v[2:17], v[112:115], v[132:135], v[2:17]
	s_cbranch_scc0 .LBB0_717
; __device__ __forceinline__ void bias_tile(f32x16& p0, f32x16& p1, int dq, const float* tb) {
; #pragma unroll
;     for (int r = 0; r < 16; ++r) {
;         const int c = (r & 3) + 8 * (r >> 2);
;         int d0 = dq - c, d1 = dq - c - 32;
;         d0 = d0 < 0 ? 0 : (d0 > 127 ? 127 : d0); d1 = d1 < 0 ? 0 : (d1 > 127 ? 127 : d1);
;         p0[r] += tb[d0]; p1[r] += tb[d1];
;     }
; }
	v_add_u32_e32 v102, -1, v99
	v_med3_i32 v103, v102, 0, v205
	v_med3_i32 v102, v102, 32, v206
	v_lshl_add_u32 v102, v102, 2, s33
	v_add_u32_e32 v104, 0xffffff80, v102
	v_add_u32_e32 v102, -2, v99
	v_med3_i32 v105, v102, 0, v205
	v_med3_i32 v102, v102, 32, v206
	v_lshl_add_u32 v102, v102, 2, s33
	v_add_u32_e32 v106, 0xffffff80, v102
	v_add_u32_e32 v102, -3, v99
	v_med3_i32 v101, v99, 32, v206
	v_med3_i32 v107, v102, 0, v205
	v_med3_i32 v102, v102, 32, v206
	v_med3_i32 v100, v99, 0, v205
	v_lshl_add_u32 v101, v101, 2, s33
	v_lshl_add_u32 v102, v102, 2, s33
	v_lshl_add_u32 v100, v100, 2, s33
	v_add_u32_e32 v101, 0xffffff80, v101
	v_lshl_add_u32 v103, v103, 2, s33
	v_lshl_add_u32 v105, v105, 2, s33
	v_lshl_add_u32 v107, v107, 2, s33
	v_add_u32_e32 v108, 0xffffff80, v102
	ds_read_b32 v100, v100
	ds_read_b32 v102, v101
	ds_read_b32 v101, v103
	ds_read_b32 v103, v104
	ds_read_b32 v104, v105
	ds_read_b32 v106, v106
	ds_read_b32 v105, v107
	ds_read_b32 v107, v108
	v_add_u32_e32 v108, -8, v99
	v_med3_i32 v109, v108, 0, v205
	v_med3_i32 v108, v108, 32, v206
	v_lshl_add_u32 v108, v108, 2, s33
	v_add_u32_e32 v110, 0xffffff80, v108
	v_add_u32_e32 v108, -9, v99
	v_med3_i32 v111, v108, 0, v205
	v_med3_i32 v108, v108, 32, v206
	v_lshl_add_u32 v108, v108, 2, s33
	v_add_u32_e32 v112, 0xffffff80, v108
	v_add_u32_e32 v108, -10, v99
	v_med3_i32 v113, v108, 0, v205
	v_med3_i32 v108, v108, 32, v206
	v_lshl_add_u32 v108, v108, 2, s33
	v_add_u32_e32 v114, 0xffffff80, v108
	v_add_u32_e32 v108, -11, v99
	v_med3_i32 v115, v108, 0, v205
	v_med3_i32 v108, v108, 32, v206
	v_lshl_add_u32 v108, v108, 2, s33
	v_lshl_add_u32 v109, v109, 2, s33
	v_lshl_add_u32 v111, v111, 2, s33
	v_lshl_add_u32 v113, v113, 2, s33
	v_lshl_add_u32 v115, v115, 2, s33
	v_add_u32_e32 v116, 0xffffff80, v108
	ds_read_b32 v108, v109
	ds_read_b32 v110, v110
	ds_read_b32 v109, v111
	ds_read_b32 v111, v112
	ds_read_b32 v112, v113
	ds_read_b32 v114, v114
	ds_read_b32 v113, v115
	ds_read_b32 v115, v116
	v_add_u32_e32 v116, -16, v99
	v_med3_i32 v117, v116, 0, v205
	v_med3_i32 v116, v116, 32, v206
	v_lshl_add_u32 v116, v116, 2, s33
	v_add_u32_e32 v118, 0xffffff80, v116
	v_subrev_u32_e32 v116, 17, v99
	v_med3_i32 v119, v116, 0, v205
	v_med3_i32 v116, v116, 32, v206
	v_lshl_add_u32 v116, v116, 2, s33
	v_add_u32_e32 v120, 0xffffff80, v116
	v_subrev_u32_e32 v116, 18, v99
	v_med3_i32 v121, v116, 0, v205
	v_med3_i32 v116, v116, 32, v206
	v_lshl_add_u32 v116, v116, 2, s33
	v_add_u32_e32 v122, 0xffffff80, v116
	v_subrev_u32_e32 v116, 19, v99
	v_med3_i32 v123, v116, 0, v205
	v_med3_i32 v116, v116, 32, v206
	v_lshl_add_u32 v116, v116, 2, s33
	v_lshl_add_u32 v117, v117, 2, s33
	v_lshl_add_u32 v119, v119, 2, s33
	v_lshl_add_u32 v121, v121, 2, s33
	v_lshl_add_u32 v123, v123, 2, s33
	v_add_u32_e32 v124, 0xffffff80, v116
	ds_read_b32 v116, v117
	ds_read_b32 v118, v118
	ds_read_b32 v117, v119
	ds_read_b32 v119, v120
	ds_read_b32 v120, v121
	ds_read_b32 v122, v122
	ds_read_b32 v121, v123
	ds_read_b32 v123, v124
	v_subrev_u32_e32 v124, 24, v99
	v_med3_i32 v125, v124, 0, v205
	v_med3_i32 v124, v124, 32, v206
	v_lshl_add_u32 v124, v124, 2, s33
	v_add_u32_e32 v126, 0xffffff80, v124
	v_subrev_u32_e32 v124, 25, v99
	v_med3_i32 v127, v124, 0, v205
	v_med3_i32 v124, v124, 32, v206
	v_lshl_add_u32 v124, v124, 2, s33
	v_add_u32_e32 v134, 0xffffff80, v124
	v_subrev_u32_e32 v124, 26, v99
	v_med3_i32 v128, v124, 0, v205
	v_med3_i32 v124, v124, 32, v206
	v_lshl_add_u32 v124, v124, 2, s33
	v_add_u32_e32 v132, 0xffffff80, v124
	v_subrev_u32_e32 v124, 27, v99
	v_med3_i32 v129, v124, 0, v205
	v_med3_i32 v124, v124, 32, v206
	v_lshl_add_u32 v124, v124, 2, s33
	v_lshl_add_u32 v125, v125, 2, s33
	v_lshl_add_u32 v127, v127, 2, s33
	v_lshl_add_u32 v128, v128, 2, s33
	v_lshl_add_u32 v129, v129, 2, s33
	v_add_u32_e32 v133, 0xffffff80, v124
	ds_read_b32 v124, v125
	ds_read_b32 v126, v126
	ds_read_b32 v128, v128
	ds_read_b32 v129, v129
	ds_read_b32 v125, v127
	ds_read_b32 v133, v133
	ds_read_b32 v132, v132
	ds_read_b32 v127, v134
	s_waitcnt lgkmcnt(4)
	v_pk_add_f32 v[96:97], v[96:97], v[128:129]
	s_waitcnt lgkmcnt(3)
	v_pk_add_f32 v[94:95], v[94:95], v[124:125]
	v_pk_add_f32 v[92:93], v[92:93], v[120:121]
	v_pk_add_f32 v[90:91], v[90:91], v[116:117]
	v_pk_add_f32 v[88:89], v[88:89], v[112:113]
	v_pk_add_f32 v[86:87], v[86:87], v[108:109]
	v_pk_add_f32 v[84:85], v[84:85], v[104:105]
	v_pk_add_f32 v[82:83], v[82:83], v[100:101]
	s_waitcnt lgkmcnt(1)
	v_pk_add_f32 v[80:81], v[80:81], v[132:133]
	s_waitcnt lgkmcnt(0)
	v_pk_add_f32 v[78:79], v[78:79], v[126:127]
	v_pk_add_f32 v[76:77], v[76:77], v[122:123]
	v_pk_add_f32 v[74:75], v[74:75], v[118:119]
	v_pk_add_f32 v[72:73], v[72:73], v[114:115]
	v_pk_add_f32 v[70:71], v[70:71], v[110:111]
	v_pk_add_f32 v[68:69], v[68:69], v[106:107]
	v_pk_add_f32 v[66:67], v[66:67], v[102:103]

; __device__ __forceinline__ void partialSM(f32x16& p0, f32x16& p1, float& m_reg, float& mn, float& alpha) {
;     ...
; #pragma unroll
;     for (int r = 0; r < 16; ++r) p0[r] = p0[r] - mn;
; #pragma unroll
;     for (int r = 0; r < 16; ++r) p1[r] = p1[r] - mn;
; #pragma unroll
;     for (int r = 0; r < 16; ++r) p0[r] = __builtin_amdgcn_exp2f(p0[r]);
; }
; __device__ __forceinline__ void finishSM(f32x16& p0, f32x16& p1, float alpha, float& l_reg, bf16x8& pa0, bf16x8& pa1, bf16x8& pa2, bf16x8& pa3) {
; #pragma unroll
;     for (int r = 0; r < 16; ++r) p1[r] = __builtin_amdgcn_exp2f(p1[r]);
;     float ps = 0;
; #pragma unroll
;     for (int r = 0; r < 16; ++r) ps += p0[r];
; #pragma unroll
;     for (int r = 0; r < 16; ++r) ps += p1[r];
;     { auto rr = __builtin_amdgcn_permlane32_swap(__float_as_uint(ps), __float_as_uint(ps), false, false);
;       ps = __uint_as_float(rr[0]) + __uint_as_float(rr[1]); }
;     l_reg = l_reg * alpha + ps;
;     ...
;     PK4(p0, 0, pa0); PK4(p0, 8, pa1); PK4(p1, 0, pa2); PK4(p1, 8, pa3);
;     ...
; }
; template <int VB>
; __device__ __forceinline__ void pv_tile(f32x16* o, int vb0, bf16x8 pa0, bf16x8 pa1, bf16x8 pa2, bf16x8 pa3) {
;     ...
;     PV_D0(0); PV_D0(1); PV_D0(2); PV_D0(3);
;     ...
; }
.LBB0_723:
	v_cndmask_b32_e64 v100, v100, v130, s[44:45]
	v_sub_f32_e32 v82, v82, v100
	v_sub_f32_e32 v83, v83, v100
	v_exp_f32_e32 v82, v82
	v_sub_f32_e32 v84, v84, v100
	v_exp_f32_e32 v83, v83
	v_sub_f32_e32 v85, v85, v100
	v_exp_f32_e32 v84, v84
	v_sub_f32_e32 v86, v86, v100
	v_sub_f32_e32 v66, v66, v100
	v_exp_f32_e32 v85, v85
	v_sub_f32_e32 v87, v87, v100
	v_sub_f32_e32 v88, v88, v100
	v_sub_f32_e32 v89, v89, v100
	v_sub_f32_e32 v90, v90, v100
	v_sub_f32_e32 v91, v91, v100
	v_sub_f32_e32 v92, v92, v100
	v_sub_f32_e32 v93, v93, v100
	v_sub_f32_e32 v94, v94, v100
	v_sub_f32_e32 v95, v95, v100
	v_sub_f32_e32 v96, v96, v100
	v_sub_f32_e32 v97, v97, v100
	v_sub_f32_e32 v67, v67, v100
	v_sub_f32_e32 v68, v68, v100
	v_sub_f32_e32 v69, v69, v100
	v_sub_f32_e32 v70, v70, v100
	v_sub_f32_e32 v71, v71, v100
	v_sub_f32_e32 v72, v72, v100
	v_sub_f32_e32 v73, v73, v100
	v_sub_f32_e32 v74, v74, v100
	v_sub_f32_e32 v75, v75, v100
	v_sub_f32_e32 v76, v76, v100
	v_sub_f32_e32 v77, v77, v100
	v_sub_f32_e32 v78, v78, v100
	v_sub_f32_e32 v79, v79, v100
	v_sub_f32_e32 v80, v80, v100
	v_sub_f32_e32 v81, v81, v100
	v_exp_f32_e32 v86, v86
	v_exp_f32_e32 v100, v66
	v_add_f32_e32 v66, 0, v82
	v_exp_f32_e32 v87, v87
	v_add_f32_e32 v66, v83, v66
	v_exp_f32_e32 v88, v88
	v_add_f32_e32 v66, v84, v66
	v_exp_f32_e32 v89, v89
	v_add_f32_e32 v66, v85, v66
	v_exp_f32_e32 v90, v90
	v_add_f32_e32 v66, v86, v66
	v_exp_f32_e32 v91, v91
	v_add_f32_e32 v66, v87, v66
	v_exp_f32_e32 v92, v92
	v_add_f32_e32 v66, v88, v66
	v_exp_f32_e32 v93, v93
	v_add_f32_e32 v66, v89, v66
	v_exp_f32_e32 v94, v94
	v_add_f32_e32 v66, v90, v66
	v_exp_f32_e32 v95, v95
	v_add_f32_e32 v66, v91, v66
	v_exp_f32_e32 v96, v96
	v_add_f32_e32 v66, v92, v66
	v_exp_f32_e32 v97, v97
	v_add_f32_e32 v66, v93, v66
	v_add_f32_e32 v66, v94, v66
	v_exp_f32_e32 v101, v67
	v_add_f32_e32 v66, v95, v66
	v_exp_f32_e32 v102, v68
	v_add_f32_e32 v66, v96, v66
	v_exp_f32_e32 v103, v69
	v_add_f32_e32 v66, v97, v66
	v_exp_f32_e32 v104, v70
	v_add_f32_e32 v66, v100, v66
	v_exp_f32_e32 v105, v71
	v_add_f32_e32 v66, v101, v66
	v_exp_f32_e32 v106, v72
	v_add_f32_e32 v66, v102, v66
	v_exp_f32_e32 v107, v73
	v_add_f32_e32 v66, v103, v66
	v_exp_f32_e32 v108, v74
	v_add_f32_e32 v66, v104, v66
	v_exp_f32_e32 v109, v75
	v_add_f32_e32 v66, v105, v66
	v_exp_f32_e32 v110, v76
	v_add_f32_e32 v66, v106, v66
	v_exp_f32_e32 v111, v77
	v_add_f32_e32 v66, v107, v66
	v_exp_f32_e32 v112, v78
	v_add_f32_e32 v66, v108, v66
	v_exp_f32_e32 v113, v79
	v_add_f32_e32 v66, v109, v66
	v_exp_f32_e32 v114, v80
	v_add_f32_e32 v66, v110, v66
	v_exp_f32_e32 v115, v81
	v_add_f32_e32 v66, v111, v66
	v_add_f32_e32 v66, v112, v66
	v_add_f32_e32 v66, v113, v66
	v_add_f32_e32 v66, v114, v66
	v_add_f32_e32 v66, v115, v66
	v_mov_b32_e32 v67, v66
	s_nop 1
	v_permlane32_swap_b32_e32 v66, v67
	v_cvt_pk_bf16_f32 v68, v82, v83
	v_cvt_pk_bf16_f32 v69, v84, v85
	v_cvt_pk_bf16_f32 v70, v86, v87
	v_cvt_pk_bf16_f32 v71, v88, v89
	v_cvt_pk_bf16_f32 v72, v90, v91
	v_cvt_pk_bf16_f32 v73, v92, v93
	v_cvt_pk_bf16_f32 v74, v94, v95
	v_cvt_pk_bf16_f32 v75, v96, v97
	v_cvt_pk_bf16_f32 v76, v100, v101
	v_cvt_pk_bf16_f32 v77, v102, v103
	v_cvt_pk_bf16_f32 v78, v104, v105
	v_cvt_pk_bf16_f32 v79, v106, v107
	v_cvt_pk_bf16_f32 v80, v108, v109
	v_cvt_pk_bf16_f32 v81, v110, v111
	v_cvt_pk_bf16_f32 v82, v112, v113
	v_cvt_pk_bf16_f32 v83, v114, v115
	s_nop 0
	v_permlane32_swap_b32_e32 v68, v70
	v_permlane32_swap_b32_e32 v69, v71
	v_permlane32_swap_b32_e32 v72, v74
	v_permlane32_swap_b32_e32 v73, v75
	v_permlane32_swap_b32_e32 v76, v78
	v_permlane32_swap_b32_e32 v77, v79
	v_permlane32_swap_b32_e32 v80, v82
	v_permlane32_swap_b32_e32 v81, v83
	ds_read_b64_tr_b16 v[84:85], v153 offset:0x4000
	ds_read_b64_tr_b16 v[86:87], v153 offset:0x4800
	ds_read_b64_tr_b16 v[88:89], v153 offset:0x5000
	ds_read_b64_tr_b16 v[90:91], v153 offset:0x5800
	ds_read_b64_tr_b16 v[92:93], v153 offset:0x6000
	ds_read_b64_tr_b16 v[94:95], v153 offset:0x6800
	ds_read_b64_tr_b16 v[100:101], v153 offset:0x7000
	ds_read_b64_tr_b16 v[102:103], v153 offset:0x7800
	s_waitcnt lgkmcnt(15)
	s_nop 0
	s_waitcnt lgkmcnt(6)
	v_mfma_f32_32x32x16_bf16 v[50:65], v[68:71], v[84:87], v[50:65]
	ds_read_b64_tr_b16 v[84:85], v153 offset:0x4200
	ds_read_b64_tr_b16 v[86:87], v153 offset:0x4a00
	s_waitcnt lgkmcnt(6)
	v_mfma_f32_32x32x16_bf16 v[50:65], v[72:75], v[88:91], v[50:65]
	ds_read_b64_tr_b16 v[88:89], v153 offset:0x5200
	ds_read_b64_tr_b16 v[90:91], v153 offset:0x5a00
	s_waitcnt lgkmcnt(6)
	v_mfma_f32_32x32x16_bf16 v[50:65], v[76:79], v[92:95], v[50:65]
	ds_read_b64_tr_b16 v[92:93], v153 offset:0x6200
	ds_read_b64_tr_b16 v[94:95], v153 offset:0x6a00
	s_waitcnt lgkmcnt(6)
	v_mfma_f32_32x32x16_bf16 v[50:65], v[80:83], v[100:103], v[50:65]
	ds_read_b64_tr_b16 v[100:101], v153 offset:0x7200
	ds_read_b64_tr_b16 v[102:103], v153 offset:0x7a00
	s_waitcnt lgkmcnt(15)
	s_waitcnt lgkmcnt(6)
	v_mfma_f32_32x32x16_bf16 v[34:49], v[68:71], v[84:87], v[34:49]
	ds_read_b64_tr_b16 v[84:85], v153 offset:0x4400
	ds_read_b64_tr_b16 v[86:87], v153 offset:0x4c00
	s_waitcnt lgkmcnt(6)
	v_mfma_f32_32x32x16_bf16 v[34:49], v[72:75], v[88:91], v[34:49]
	ds_read_b64_tr_b16 v[88:89], v153 offset:0x5400
	ds_read_b64_tr_b16 v[90:91], v153 offset:0x5c00
	s_waitcnt lgkmcnt(6)
	v_mfma_f32_32x32x16_bf16 v[34:49], v[76:79], v[92:95], v[34:49]
	ds_read_b64_tr_b16 v[92:93], v153 offset:0x6400
	ds_read_b64_tr_b16 v[94:95], v153 offset:0x6c00
	s_waitcnt lgkmcnt(6)
	v_mfma_f32_32x32x16_bf16 v[34:49], v[80:83], v[100:103], v[34:49]
	ds_read_b64_tr_b16 v[100:101], v153 offset:0x7400
	ds_read_b64_tr_b16 v[102:103], v153 offset:0x7c00
	s_waitcnt lgkmcnt(15)
	s_waitcnt lgkmcnt(6)
	v_mfma_f32_32x32x16_bf16 v[18:33], v[68:71], v[84:87], v[18:33]
	ds_read_b64_tr_b16 v[84:85], v153 offset:0x4600
	ds_read_b64_tr_b16 v[86:87], v153 offset:0x4e00
	s_waitcnt lgkmcnt(6)
	v_mfma_f32_32x32x16_bf16 v[18:33], v[72:75], v[88:91], v[18:33]
	ds_read_b64_tr_b16 v[88:89], v153 offset:0x5600
	ds_read_b64_tr_b16 v[90:91], v153 offset:0x5e00
	s_waitcnt lgkmcnt(6)
	v_mfma_f32_32x32x16_bf16 v[18:33], v[76:79], v[92:95], v[18:33]
	ds_read_b64_tr_b16 v[92:93], v153 offset:0x6600
	ds_read_b64_tr_b16 v[94:95], v153 offset:0x6e00
	s_waitcnt lgkmcnt(6)
	v_mfma_f32_32x32x16_bf16 v[18:33], v[80:83], v[100:103], v[18:33]
	ds_read_b64_tr_b16 v[100:101], v153 offset:0x7600
	ds_read_b64_tr_b16 v[102:103], v153 offset:0x7e00
	s_waitcnt lgkmcnt(15)
	s_waitcnt lgkmcnt(6)
	v_mfma_f32_32x32x16_bf16 v[2:17], v[68:71], v[84:87], v[2:17]
	s_waitcnt lgkmcnt(4)
	v_mfma_f32_32x32x16_bf16 v[2:17], v[72:75], v[88:91], v[2:17]
	s_waitcnt lgkmcnt(2)
	v_mfma_f32_32x32x16_bf16 v[2:17], v[76:79], v[92:95], v[2:17]
	s_waitcnt lgkmcnt(0)
	v_mfma_f32_32x32x16_bf16 v[2:17], v[80:83], v[100:103], v[2:17]
	s_barrier
; __device__ __forceinline__ float lane_xor1(float v) { return __builtin_bit_cast(float, __builtin_amdgcn_update_dpp(0, __builtin_bit_cast(int, v), 0xB1, 0xF, 0xF, false)); }
; __device__ __forceinline__ int crow(int r, int hi) { return (r & 3) + 8 * (r >> 2) + 4 * hi; }
; __device__ __forceinline__ unsigned cvtpk(float lo, float hi) { unsigned r; asm volatile("v_cvt_pk_bf16_f32 %0, %1, %2" : "=v"(r) : "v"(lo), "v"(hi)); return r; }
; template <bool MLA, int MODE, bool PIPE>
; __device__ __forceinline__ void attn_block(const AttnArgs& a, char* lds) {
;     ...
;     if (hi == 0) li_l[r32] = l_reg; asm volatile("s_waitcnt lgkmcnt(0)" ::: "memory");
;     float rli[16];
; #pragma unroll
;     for (int r = 0; r < 16; ++r) rli[r] = __builtin_amdgcn_rcpf(li_l[crow(r, hi)]);
;     if constexpr (MODE == 0) {
;         bf16_t* Ow = a.Out + (size_t)qlo * 1024;
; #pragma unroll
;         for (int r = 0; r < 16; ++r) { const int orow = crow(r, hi);
; #pragma unroll
;             for (int d0 = 0; d0 < 4; ++d0) { const float v = o[d0][r] * rli[r]; const float vn = lane_xor1(v);
;                 if ((r32 & 1) == 0) *(unsigned*)(Ow + (size_t)orow * 1024 + d0 * 32 + r32) = cvtpk(v, vn); } }
;     } else if constexpr (MODE == 1) {
;         bf16_t* Ow = (bf16_t*)a.O0 + (size_t)qlo * 512;
; #pragma unroll
;         for (int r = 0; r < 16; ++r) { const int orow = crow(r, hi);
; #pragma unroll
;             for (int d0 = 0; d0 < 4; ++d0) { const float v = o[d0][r] * rli[r]; const float vn = lane_xor1(v);
;                 if ((r32 & 1) == 0) *(unsigned*)(Ow + (size_t)orow * 512 + d0 * 32 + r32) = cvtpk(v, vn); } }
	s_and_saveexec_b64 s[4:5], s[42:43]
	v_add_f32_e32 v0, v0, v98
	v_fmac_f32_e32 v0, v156, v131
	v_add_f32_e32 v66, v66, v67
	v_fmac_f32_e32 v66, v0, v99
	ds_write_b32 v155, v66
	s_or_b64 exec, exec, s[4:5]
	s_add_u32 s4, s14, s24
	s_addc_u32 s5, s15, s25
	s_add_u32 s4, s4, s2
	s_waitcnt lgkmcnt(0)
	s_addc_u32 s5, s5, s3
	s_lshl_b64 s[2:3], s[0:1], 22
	ds_read_b128 v[78:81], v154
	ds_read_b128 v[74:77], v154 offset:32
	s_add_u32 s4, s4, s2
	s_addc_u32 s5, s5, s3
	s_lshl_b32 s6, s29, 1
	s_add_u32 s6, s4, s6
	s_addc_u32 s7, s5, 0
	s_ashr_i32 s31, s30, 31
	s_waitcnt lgkmcnt(1)
	v_rcp_f32_e32 v78, v78
	s_lshl_b64 s[4:5], s[30:31], 10
	ds_read_b128 v[70:73], v154 offset:64
	ds_read_b128 v[66:69], v154 offset:96
	s_add_u32 s4, s6, s4
	v_and_b32_e32 v0, 1, v151
	s_addc_u32 s5, s7, s5
	v_cmp_eq_u32_e64 s[42:43], 0, v0
	v_lshlrev_b32_e32 v0, 1, v152
	v_lshl_add_u64 v[82:83], s[4:5], 0, v[0:1]
	v_lshlrev_b32_e32 v0, 12, v150
	v_lshl_add_u64 v[82:83], v[82:83], 0, v[0:1]
	v_mul_f32_e32 v0, v50, v78
	v_mov_b32_e32 v50, v1
	s_nop 1
	v_mov_b32_dpp v50, v0 quad_perm:[1,0,3,2] row_mask:0xf bank_mask:0xf
	s_and_saveexec_b64 s[4:5], s[42:43]
	s_cbranch_execz .LBB0_727
	v_cvt_pk_bf16_f32 v0, v0, v50
	global_store_dword v[82:83], v0, off
